# SSM pass C rewritten by hand: plain f32 fma scan (no SLP-packed ops / shuffles), C fragments loaded once per item, lane exchanges batched
# speedup vs baseline: 1.0350x; 1.0140x over previous
.LBB0_1386:
	s_or_b64 exec, exec, s[0:1]
	v_readlane_b32 s2, v255, 3
	v_readlane_b32 s3, v255, 4
	s_waitcnt lgkmcnt(0)
	v_mov_b32_e32 v2, v0
	v_readlane_b32 s0, v255, 7
	s_barrier
	s_cmpk_gt_i32 s0, 0x3ff
	v_readfirstlane_b32 s6, v2
	s_cbranch_scc1 .LBB0_1414
	s_cmp_eq_u32 s97, 0x100
	s_cbranch_scc0 .Lpc_compiled
	v_readlane_b32 s6, v255, 3
	v_readlane_b32 s7, v255, 4
	v_readlane_b32 s46, v255, 7
	v_readlane_b32 s47, v255, 2
	s_nop 4
	s_load_dwordx4 s[8:11], s[6:7], 0xc8
	s_load_dwordx2 s[12:13], s[6:7], 0xa0
	s_lshr_b32 s47, s47, 6
	s_lshl_b32 s48, s47, 13
	s_mov_b32 s42, -1
	s_mov_b32 s43, 0
	s_mov_b32 s44, 0xffff
	s_mov_b32 s45, 0xffff
	v_and_b32_e32 v209, 63, v0
	v_and_b32_e32 v210, 31, v209
	v_lshrrev_b32_e32 v211, 5, v209
	v_cmp_lt_u32_e64 s[40:41], 31, v209
	v_xor_b32_e32 v199, 32, v209
	v_lshlrev_b32_e32 v199, 2, v199
	v_lshlrev_b32_e32 v200, 6, v210
	v_lshl_add_u32 v200, v211, 3, v200
	v_add_u32_e32 v200, s48, v200
	v_and_b32_e32 v212, 15, v209
	v_lshrrev_b32_e32 v213, 2, v212
	v_and_b32_e32 v212, 3, v212
	v_bfe_u32 v214, v209, 4, 1
	v_lshl_add_u32 v213, v211, 3, v213
	v_lshlrev_b32_e32 v201, 6, v213
	v_lshl_add_u32 v212, v214, 2, v212
	v_lshl_add_u32 v201, v212, 3, v201
	v_add_u32_e32 v201, s48, v201
	v_lshlrev_b32_e32 v202, 2, v210
	v_lshl_add_u32 v202, v211, 8, v202
	v_add_u32_e32 v202, s48, v202
	v_lshrrev_b32_e32 v212, 1, v209
	v_and_b32_e32 v213, 1, v209
	v_lshlrev_b32_e32 v203, 6, v212
	v_lshl_add_u32 v203, v213, 5, v203
	v_add_u32_e32 v203, s48, v203
	v_lshlrev_b32_e32 v204, 12, v210
	v_lshl_add_u32 v204, v211, 4, v204
	v_lshlrev_b32_e32 v205, 12, v212
	v_lshl_add_u32 v205, v213, 4, v205
	v_lshlrev_b32_e32 v206, 2, v210
	v_lshlrev_b32_e32 v207, 3, v210
	v_lshlrev_b32_e32 v208, 4, v209
	v_lshlrev_b32_e32 v212, 3, v211
	v_sub_u32_e32 v212, v210, v212
	s_waitcnt lgkmcnt(0)
	v_mov_b32_e32 v254, v212
	v_cmp_gt_u32_e64 s[38:39], 16, v210
.Lpc_item:
	s_and_b32 s14, s46, 15
	s_lshl_b32 s14, s14, 3
	s_add_i32 s14, s14, s47
	s_bfe_u32 s15, s46, 0x50004
	s_lshr_b32 s18, s46, 9
	s_lshl_b32 s20, s14, 9
	s_add_u32 s52, s10, 0x30000
	s_addc_u32 s53, s11, 0
	s_add_u32 s52, s52, s20
	s_addc_u32 s53, s53, 0
	s_lshl_b32 s20, s14, 12
	s_add_u32 s54, s10, 0x140000
	s_addc_u32 s55, s11, 0
	s_add_u32 s54, s54, s20
	s_addc_u32 s55, s55, 0
	s_lshl_b32 s20, s14, 13
	s_add_u32 s56, s10, 0x1c0000
	s_addc_u32 s57, s11, 0
	s_add_u32 s56, s56, s20
	s_addc_u32 s57, s57, 0
	s_lshl_b32 s20, s18, 24
	s_lshl_b32 s25, s15, 19
	s_add_i32 s20, s20, s25
	s_lshl_b32 s25, s14, 5
	s_add_i32 s20, s20, s25
	s_add_u32 s58, s10, 0x5200000
	s_addc_u32 s59, s11, 0
	s_add_u32 s58, s58, s20
	s_addc_u32 s59, s59, 0
	s_add_u32 s60, s10, 0xd600000
	s_addc_u32 s61, s11, 0
	s_add_u32 s60, s60, s20
	s_addc_u32 s61, s61, 0
	s_lshl_b32 s20, s18, 7
	s_add_i32 s20, s20, s14
	s_lshl_b32 s25, s20, 14
	s_add_u32 s62, s10, 0x600000
	s_addc_u32 s63, s11, 0
	s_add_u32 s62, s62, s25
	s_addc_u32 s63, s63, 0
	s_lshl_b32 s25, s20, 8
	s_add_u32 s64, s8, 0x6084000
	s_addc_u32 s65, s9, 0
	s_add_u32 s64, s64, s25
	s_addc_u32 s65, s65, 0
	s_add_u32 s66, s8, 0x6094000
	s_addc_u32 s67, s9, 0
	s_add_u32 s66, s66, s25
	s_addc_u32 s67, s67, 0
	s_lshl_b32 s25, s14, 6
	s_add_u32 s68, s12, s25
	s_addc_u32 s69, s13, 0
	s_lshr_b32 s26, s15, 2
	s_and_b32 s27, s15, 3
	global_load_dwordx2 v[6:7], v207, s[52:53]
	global_load_dwordx2 v[14:15], v207, s[52:53] offset:256
	s_add_u32 s70, s62, 0x600
	s_addc_u32 s71, s63, 0
	global_load_dword v46, v206, s[70:71] offset:0
	global_load_dword v47, v206, s[70:71] offset:256
	global_load_dword v48, v206, s[70:71] offset:128
	global_load_dword v49, v206, s[70:71] offset:384
	s_add_u32 s70, s62, 0xe00
	s_addc_u32 s71, s63, 0
	global_load_dword v50, v206, s[70:71] offset:0
	global_load_dword v51, v206, s[70:71] offset:256
	global_load_dword v52, v206, s[70:71] offset:128
	global_load_dword v53, v206, s[70:71] offset:384
	s_add_u32 s70, s62, 0x1600
	s_addc_u32 s71, s63, 0
	global_load_dword v54, v206, s[70:71] offset:0
	global_load_dword v55, v206, s[70:71] offset:256
	global_load_dword v56, v206, s[70:71] offset:128
	global_load_dword v57, v206, s[70:71] offset:384
	s_add_u32 s70, s62, 0x1e00
	s_addc_u32 s71, s63, 0
	global_load_dword v58, v206, s[70:71] offset:0
	global_load_dword v59, v206, s[70:71] offset:256
	global_load_dword v60, v206, s[70:71] offset:128
	global_load_dword v61, v206, s[70:71] offset:384
	s_add_u32 s70, s62, 0x2600
	s_addc_u32 s71, s63, 0
	global_load_dword v62, v206, s[70:71] offset:0
	global_load_dword v63, v206, s[70:71] offset:256
	global_load_dword v64, v206, s[70:71] offset:128
	global_load_dword v65, v206, s[70:71] offset:384
	s_add_u32 s70, s62, 0x2e00
	s_addc_u32 s71, s63, 0
	global_load_dword v66, v206, s[70:71] offset:0
	global_load_dword v67, v206, s[70:71] offset:256
	global_load_dword v68, v206, s[70:71] offset:128
	global_load_dword v69, v206, s[70:71] offset:384
	s_add_u32 s70, s62, 0x3600
	s_addc_u32 s71, s63, 0
	global_load_dword v70, v206, s[70:71] offset:0
	global_load_dword v71, v206, s[70:71] offset:256
	global_load_dword v72, v206, s[70:71] offset:128
	global_load_dword v73, v206, s[70:71] offset:384
	s_add_i32 s25, s15, -1
	s_lshl_b32 s25, s25, 9
	s_ashr_i32 s29, s25, 31
	s_add_u32 s70, s62, s25
	s_addc_u32 s71, s63, s29
	global_load_dword v74, v206, s[70:71] offset:0
	global_load_dword v75, v206, s[70:71] offset:256
	global_load_dword v76, v206, s[70:71] offset:128
	global_load_dword v77, v206, s[70:71] offset:384
	global_load_dwordx4 v[26:29], v208, s[54:55] offset:0
	global_load_dwordx4 v[30:33], v208, s[54:55] offset:1024
	global_load_dwordx4 v[34:37], v208, s[54:55] offset:2048
	global_load_dwordx4 v[38:41], v208, s[54:55] offset:3072
	v_and_b32_e32 v209, 60, v206
	global_load_dword v210, v209, s[68:69]
	global_load_dwordx4 v[126:129], v204, s[58:59]
	s_add_u32 s70, s56, 0x0
	s_addc_u32 s71, s57, 0
	global_load_dwordx4 v[134:137], v208, s[70:71] offset:0
	s_add_u32 s70, s56, 0x0
	s_addc_u32 s71, s57, 0
	global_load_dwordx4 v[138:141], v208, s[70:71] offset:1024
	s_add_u32 s70, s56, 0x0
	s_addc_u32 s71, s57, 0
	global_load_dwordx4 v[142:145], v208, s[70:71] offset:2048
	s_add_u32 s70, s56, 0x0
	s_addc_u32 s71, s57, 0
	global_load_dwordx4 v[146:149], v208, s[70:71] offset:3072
	s_add_u32 s70, s56, 0x1000
	s_addc_u32 s71, s57, 0
	global_load_dwordx4 v[150:153], v208, s[70:71] offset:0
	s_add_u32 s70, s56, 0x1000
	s_addc_u32 s71, s57, 0
	global_load_dwordx4 v[154:157], v208, s[70:71] offset:1024
	s_add_u32 s70, s56, 0x1000
	s_addc_u32 s71, s57, 0
	global_load_dwordx4 v[158:161], v208, s[70:71] offset:2048
	s_add_u32 s70, s56, 0x1000
	s_addc_u32 s71, s57, 0
	global_load_dwordx4 v[162:165], v208, s[70:71] offset:3072
	s_waitcnt vmcnt(47)
	v_mul_f32_e32 v98, v7, v7
	v_fma_f32 v8, v6, v6, -v98
	v_mul_f32_e32 v98, v7, v6
	v_fma_f32 v9, v6, v7, v98
	v_mul_f32_e32 v98, v9, v7
	v_fma_f32 v10, v8, v6, -v98
	v_mul_f32_e32 v98, v9, v6
	v_fma_f32 v11, v8, v7, v98
	v_mul_f32_e32 v98, v9, v9
	v_fma_f32 v12, v8, v8, -v98
	v_mul_f32_e32 v98, v9, v8
	v_fma_f32 v13, v8, v9, v98
	v_mul_f32_e32 v98, v13, v13
	v_fma_f32 v94, v12, v12, -v98
	v_mul_f32_e32 v98, v13, v12
	v_fma_f32 v95, v12, v13, v98
	v_mul_f32_e32 v98, v95, v95
	v_fma_f32 v96, v94, v94, -v98
	v_mul_f32_e32 v98, v95, v94
	v_fma_f32 v97, v94, v95, v98
	v_mul_f32_e32 v98, v97, v97
	v_fma_f32 v94, v96, v96, -v98
	v_mul_f32_e32 v98, v97, v96
	v_fma_f32 v95, v96, v97, v98
	v_mul_f32_e32 v98, v95, v95
	v_fma_f32 v96, v94, v94, -v98
	v_mul_f32_e32 v98, v95, v94
	v_fma_f32 v97, v94, v95, v98
	v_mul_f32_e32 v98, v97, v97
	v_fma_f32 v78, v96, v96, -v98
	v_mul_f32_e32 v98, v97, v96
	v_fma_f32 v79, v96, v97, v98
	v_mul_f32_e32 v98, v79, v79
	v_fma_f32 v82, v78, v78, -v98
	v_mul_f32_e32 v98, v79, v78
	v_fma_f32 v83, v78, v79, v98
	v_mul_f32_e32 v98, v83, v83
	v_fma_f32 v86, v82, v82, -v98
	v_mul_f32_e32 v98, v83, v82
	v_fma_f32 v87, v82, v83, v98
	v_mul_f32_e32 v98, v83, v79
	v_fma_f32 v90, v82, v78, -v98
	v_mul_f32_e32 v98, v83, v78
	v_fma_f32 v91, v82, v79, v98
	s_waitcnt vmcnt(46)
	v_mul_f32_e32 v98, v15, v15
	v_fma_f32 v16, v14, v14, -v98
	v_mul_f32_e32 v98, v15, v14
	v_fma_f32 v17, v14, v15, v98
	v_mul_f32_e32 v98, v17, v15
	v_fma_f32 v18, v16, v14, -v98
	v_mul_f32_e32 v98, v17, v14
	v_fma_f32 v19, v16, v15, v98
	v_mul_f32_e32 v98, v17, v17
	v_fma_f32 v20, v16, v16, -v98
	v_mul_f32_e32 v98, v17, v16
	v_fma_f32 v21, v16, v17, v98
	v_mul_f32_e32 v98, v21, v21
	v_fma_f32 v94, v20, v20, -v98
	v_mul_f32_e32 v98, v21, v20
	v_fma_f32 v95, v20, v21, v98
	v_mul_f32_e32 v98, v95, v95
	v_fma_f32 v96, v94, v94, -v98
	v_mul_f32_e32 v98, v95, v94
	v_fma_f32 v97, v94, v95, v98
	v_mul_f32_e32 v98, v97, v97
	v_fma_f32 v94, v96, v96, -v98
	v_mul_f32_e32 v98, v97, v96
	v_fma_f32 v95, v96, v97, v98
	v_mul_f32_e32 v98, v95, v95
	v_fma_f32 v96, v94, v94, -v98
	v_mul_f32_e32 v98, v95, v94
	v_fma_f32 v97, v94, v95, v98
	v_mul_f32_e32 v98, v97, v97
	v_fma_f32 v80, v96, v96, -v98
	v_mul_f32_e32 v98, v97, v96
	v_fma_f32 v81, v96, v97, v98
	v_mul_f32_e32 v98, v81, v81
	v_fma_f32 v84, v80, v80, -v98
	v_mul_f32_e32 v98, v81, v80
	v_fma_f32 v85, v80, v81, v98
	v_mul_f32_e32 v98, v85, v85
	v_fma_f32 v88, v84, v84, -v98
	v_mul_f32_e32 v98, v85, v84
	v_fma_f32 v89, v84, v85, v98
	v_mul_f32_e32 v98, v85, v81
	v_fma_f32 v92, v84, v80, -v98
	v_mul_f32_e32 v98, v85, v80
	v_fma_f32 v93, v84, v81, v98
	v_mov_b32_e32 v22, 0
	v_mov_b32_e32 v23, 0
	v_mov_b32_e32 v24, 0
	v_mov_b32_e32 v25, 0
	s_cmp_gt_u32 s26, 0
	s_cbranch_scc0 .Lpc_cq_done
	s_waitcnt vmcnt(42)
	v_fma_f32 v211, -v87, v23, v46
	v_fma_f32 v212, v87, v22, v47
	v_fma_f32 v22, v86, v22, v211
	v_fma_f32 v23, v86, v23, v212
	v_fma_f32 v211, -v89, v25, v48
	v_fma_f32 v212, v89, v24, v49
	v_fma_f32 v24, v88, v24, v211
	v_fma_f32 v25, v88, v25, v212
	s_cmp_gt_u32 s26, 1
	s_cbranch_scc0 .Lpc_cq_done
	s_waitcnt vmcnt(38)
	v_fma_f32 v211, -v87, v23, v50
	v_fma_f32 v212, v87, v22, v51
	v_fma_f32 v22, v86, v22, v211
	v_fma_f32 v23, v86, v23, v212
	v_fma_f32 v211, -v89, v25, v52
	v_fma_f32 v212, v89, v24, v53
	v_fma_f32 v24, v88, v24, v211
	v_fma_f32 v25, v88, v25, v212
	s_cmp_gt_u32 s26, 2
	s_cbranch_scc0 .Lpc_cq_done
	s_waitcnt vmcnt(34)
	v_fma_f32 v211, -v87, v23, v54
	v_fma_f32 v212, v87, v22, v55
	v_fma_f32 v22, v86, v22, v211
	v_fma_f32 v23, v86, v23, v212
	v_fma_f32 v211, -v89, v25, v56
	v_fma_f32 v212, v89, v24, v57
	v_fma_f32 v24, v88, v24, v211
	v_fma_f32 v25, v88, v25, v212
	s_cmp_gt_u32 s26, 3
	s_cbranch_scc0 .Lpc_cq_done
	s_waitcnt vmcnt(30)
	v_fma_f32 v211, -v87, v23, v58
	v_fma_f32 v212, v87, v22, v59
	v_fma_f32 v22, v86, v22, v211
	v_fma_f32 v23, v86, v23, v212
	v_fma_f32 v211, -v89, v25, v60
	v_fma_f32 v212, v89, v24, v61
	v_fma_f32 v24, v88, v24, v211
	v_fma_f32 v25, v88, v25, v212
	s_cmp_gt_u32 s26, 4
	s_cbranch_scc0 .Lpc_cq_done
	s_waitcnt vmcnt(26)
	v_fma_f32 v211, -v87, v23, v62
	v_fma_f32 v212, v87, v22, v63
	v_fma_f32 v22, v86, v22, v211
	v_fma_f32 v23, v86, v23, v212
	v_fma_f32 v211, -v89, v25, v64
	v_fma_f32 v212, v89, v24, v65
	v_fma_f32 v24, v88, v24, v211
	v_fma_f32 v25, v88, v25, v212
	s_cmp_gt_u32 s26, 5
	s_cbranch_scc0 .Lpc_cq_done
	s_waitcnt vmcnt(22)
	v_fma_f32 v211, -v87, v23, v66
	v_fma_f32 v212, v87, v22, v67
	v_fma_f32 v22, v86, v22, v211
	v_fma_f32 v23, v86, v23, v212
	v_fma_f32 v211, -v89, v25, v68
	v_fma_f32 v212, v89, v24, v69
	v_fma_f32 v24, v88, v24, v211
	v_fma_f32 v25, v88, v25, v212
	s_cmp_gt_u32 s26, 6
	s_cbranch_scc0 .Lpc_cq_done
	s_waitcnt vmcnt(18)
	v_fma_f32 v211, -v87, v23, v70
	v_fma_f32 v212, v87, v22, v71
	v_fma_f32 v22, v86, v22, v211
	v_fma_f32 v23, v86, v23, v212
	v_fma_f32 v211, -v89, v25, v72
	v_fma_f32 v212, v89, v24, v73
	v_fma_f32 v24, v88, v24, v211
	v_fma_f32 v25, v88, v25, v212
.Lpc_cq_done:
	s_cmp_eq_u32 s27, 0
	s_cbranch_scc1 .Lpc_kq_done
	s_waitcnt vmcnt(14)
	s_cmp_eq_u32 s27, 1
	s_cbranch_scc1 .Lpc_kq1
	s_cmp_eq_u32 s27, 2
	s_cbranch_scc1 .Lpc_kq2
	v_fma_f32 v211, -v91, v23, v74
	v_fma_f32 v212, v91, v22, v75
	v_fma_f32 v22, v90, v22, v211
	v_fma_f32 v23, v90, v23, v212
	v_fma_f32 v211, -v93, v25, v76
	v_fma_f32 v212, v93, v24, v77
	v_fma_f32 v24, v92, v24, v211
	v_fma_f32 v25, v92, v25, v212
	s_branch .Lpc_kq_done
.Lpc_kq1:
	v_fma_f32 v211, -v79, v23, v74
	v_fma_f32 v212, v79, v22, v75
	v_fma_f32 v22, v78, v22, v211
	v_fma_f32 v23, v78, v23, v212
	v_fma_f32 v211, -v81, v25, v76
	v_fma_f32 v212, v81, v24, v77
	v_fma_f32 v24, v80, v24, v211
	v_fma_f32 v25, v80, v25, v212
	s_branch .Lpc_kq_done
.Lpc_kq2:
	v_fma_f32 v211, -v83, v23, v74
	v_fma_f32 v212, v83, v22, v75
	v_fma_f32 v22, v82, v22, v211
	v_fma_f32 v23, v82, v23, v212
	v_fma_f32 v211, -v85, v25, v76
	v_fma_f32 v212, v85, v24, v77
	v_fma_f32 v24, v84, v24, v211
	v_fma_f32 v25, v84, v25, v212
.Lpc_kq_done:
	s_waitcnt vmcnt(9)
	v_cndmask_b32_e64 v210, 0, v210, s[38:39]
	v_cvt_pk_bf16_f32 v210, v210, 0
	v_and_b32_e32 v210, 0xffff, v210
	v_and_b32_e32 v211, 1, v254
	v_lshlrev_b32_e32 v211, 4, v211
	v_lshlrev_b32_e32 v210, v211, v210
	v_ashrrev_i32_e32 v211, 1, v254
	v_cmp_eq_u32_e32 vcc, 0, v211
	s_nop 1
	v_cndmask_b32_e32 v42, 0, v210, vcc
	v_cmp_eq_u32_e32 vcc, 1, v211
	s_nop 1
	v_cndmask_b32_e32 v43, 0, v210, vcc
	v_cmp_eq_u32_e32 vcc, 2, v211
	s_nop 1
	v_cndmask_b32_e32 v44, 0, v210, vcc
	v_cmp_eq_u32_e32 vcc, 3, v211
	s_nop 1
	v_cndmask_b32_e32 v45, 0, v210, vcc
	s_waitcnt vmcnt(0)
	v_mfma_f32_32x32x16_bf16 v[46:61], v[126:129], v[26:29], 0
	v_mfma_f32_32x32x16_bf16 v[78:93], v[126:129], v[34:37], 0
	v_mfma_f32_32x32x16_bf16 v[62:77], v[126:129], v[30:33], 0
	v_mfma_f32_32x32x16_bf16 v[94:109], v[126:129], v[38:41], 0
	v_mfma_f32_32x32x16_bf16 v[110:125], v[126:129], v[42:45], 0
	s_add_u32 s70, s58, 0x20000
	s_addc_u32 s71, s59, 0
	global_load_dwordx4 v[130:133], v204, s[70:71]
	s_nop 7
	s_nop 1
	v_fmac_f32_e32 v47, v6, v46
	v_fmac_f32_e32 v79, v6, v78
	v_fma_f32 v47, -v7, v78, v47
	v_fmac_f32_e32 v79, v7, v46
	v_fmac_f32_e32 v51, v6, v50
	v_fmac_f32_e32 v83, v6, v82
	v_fma_f32 v51, -v7, v82, v51
	v_fmac_f32_e32 v83, v7, v50
	v_fmac_f32_e32 v55, v6, v54
	v_fmac_f32_e32 v87, v6, v86
	v_fma_f32 v55, -v7, v86, v55
	v_fmac_f32_e32 v87, v7, v54
	v_fmac_f32_e32 v59, v6, v58
	v_fmac_f32_e32 v91, v6, v90
	v_fma_f32 v59, -v7, v90, v59
	v_fmac_f32_e32 v91, v7, v58
	v_fmac_f32_e32 v63, v14, v62
	v_fmac_f32_e32 v95, v14, v94
	v_fma_f32 v63, -v15, v94, v63
	v_fmac_f32_e32 v95, v15, v62
	v_fmac_f32_e32 v67, v14, v66
	v_fmac_f32_e32 v99, v14, v98
	v_fma_f32 v67, -v15, v98, v67
	v_fmac_f32_e32 v99, v15, v66
	v_fmac_f32_e32 v71, v14, v70
	v_fmac_f32_e32 v103, v14, v102
	v_fma_f32 v71, -v15, v102, v71
	v_fmac_f32_e32 v103, v15, v70
	v_fmac_f32_e32 v75, v14, v74
	v_fmac_f32_e32 v107, v14, v106
	v_fma_f32 v75, -v15, v106, v75
	v_fmac_f32_e32 v107, v15, v74
	v_fmac_f32_e32 v48, v6, v47
	v_fmac_f32_e32 v80, v6, v79
	v_fma_f32 v48, -v7, v79, v48
	v_fmac_f32_e32 v80, v7, v47
	v_fmac_f32_e32 v52, v6, v51
	v_fmac_f32_e32 v84, v6, v83
	v_fma_f32 v52, -v7, v83, v52
	v_fmac_f32_e32 v84, v7, v51
	v_fmac_f32_e32 v56, v6, v55
	v_fmac_f32_e32 v88, v6, v87
	v_fma_f32 v56, -v7, v87, v56
	v_fmac_f32_e32 v88, v7, v55
	v_fmac_f32_e32 v60, v6, v59
	v_fmac_f32_e32 v92, v6, v91
	v_fma_f32 v60, -v7, v91, v60
	v_fmac_f32_e32 v92, v7, v59
	v_fmac_f32_e32 v64, v14, v63
	v_fmac_f32_e32 v96, v14, v95
	v_fma_f32 v64, -v15, v95, v64
	v_fmac_f32_e32 v96, v15, v63
	v_fmac_f32_e32 v68, v14, v67
	v_fmac_f32_e32 v100, v14, v99
	v_fma_f32 v68, -v15, v99, v68
	v_fmac_f32_e32 v100, v15, v67
	v_fmac_f32_e32 v72, v14, v71
	v_fmac_f32_e32 v104, v14, v103
	v_fma_f32 v72, -v15, v103, v72
	v_fmac_f32_e32 v104, v15, v71
	v_fmac_f32_e32 v76, v14, v75
	v_fmac_f32_e32 v108, v14, v107
	v_fma_f32 v76, -v15, v107, v76
	v_fmac_f32_e32 v108, v15, v75
	v_fmac_f32_e32 v49, v6, v48
	v_fmac_f32_e32 v81, v6, v80
	v_fma_f32 v49, -v7, v80, v49
	v_fmac_f32_e32 v81, v7, v48
	v_fmac_f32_e32 v53, v6, v52
	v_fmac_f32_e32 v85, v6, v84
	v_fma_f32 v53, -v7, v84, v53
	v_fmac_f32_e32 v85, v7, v52
	v_fmac_f32_e32 v57, v6, v56
	v_fmac_f32_e32 v89, v6, v88
	v_fma_f32 v57, -v7, v88, v57
	v_fmac_f32_e32 v89, v7, v56
	v_fmac_f32_e32 v61, v6, v60
	v_fmac_f32_e32 v93, v6, v92
	v_fma_f32 v61, -v7, v92, v61
	v_fmac_f32_e32 v93, v7, v60
	v_fmac_f32_e32 v65, v14, v64
	v_fmac_f32_e32 v97, v14, v96
	v_fma_f32 v65, -v15, v96, v65
	v_fmac_f32_e32 v97, v15, v64
	v_fmac_f32_e32 v69, v14, v68
	v_fmac_f32_e32 v101, v14, v100
	v_fma_f32 v69, -v15, v100, v69
	v_fmac_f32_e32 v101, v15, v68
	v_fmac_f32_e32 v73, v14, v72
	v_fmac_f32_e32 v105, v14, v104
	v_fma_f32 v73, -v15, v104, v73
	v_fmac_f32_e32 v105, v15, v72
	v_fmac_f32_e32 v77, v14, v76
	v_fmac_f32_e32 v109, v14, v108
	v_fma_f32 v77, -v15, v108, v77
	v_fmac_f32_e32 v109, v15, v76
	ds_bpermute_b32 v167, v199, v49
	ds_bpermute_b32 v168, v199, v81
	ds_bpermute_b32 v169, v199, v53
	ds_bpermute_b32 v170, v199, v85
	ds_bpermute_b32 v171, v199, v57
	ds_bpermute_b32 v172, v199, v89
	ds_bpermute_b32 v173, v199, v61
	ds_bpermute_b32 v174, v199, v93
	ds_bpermute_b32 v175, v199, v65
	ds_bpermute_b32 v176, v199, v97
	ds_bpermute_b32 v177, v199, v69
	ds_bpermute_b32 v178, v199, v101
	ds_bpermute_b32 v179, v199, v73
	ds_bpermute_b32 v180, v199, v105
	ds_bpermute_b32 v181, v199, v77
	ds_bpermute_b32 v182, v199, v109
	s_waitcnt lgkmcnt(0)
	v_cndmask_b32_e64 v216, v49, v167, s[40:41]
	v_cndmask_b32_e64 v217, v81, v168, s[40:41]
	v_cndmask_b32_e64 v218, v167, v49, s[40:41]
	v_cndmask_b32_e64 v219, v168, v81, s[40:41]
	v_fma_f32 v213, v12, v22, v216
	v_fma_f32 v214, v12, v23, v217
	v_fma_f32 v213, -v13, v23, v213
	v_fmac_f32_e32 v214, v13, v22
	v_fma_f32 v215, v12, v213, v218
	v_fma_f32 v248, v12, v214, v219
	v_fma_f32 v215, -v13, v214, v215
	v_fmac_f32_e32 v248, v13, v213
	v_cndmask_b32_e64 v183, v22, v213, s[40:41]
	v_cndmask_b32_e64 v184, v23, v214, s[40:41]
	v_cndmask_b32_e64 v224, v65, v175, s[40:41]
	v_cndmask_b32_e64 v225, v97, v176, s[40:41]
	v_cndmask_b32_e64 v226, v175, v65, s[40:41]
	v_cndmask_b32_e64 v227, v176, v97, s[40:41]
	v_fma_f32 v251, v20, v24, v224
	v_fma_f32 v252, v20, v25, v225
	v_fma_f32 v251, -v21, v25, v251
	v_fmac_f32_e32 v252, v21, v24
	v_fma_f32 v253, v20, v251, v226
	v_fma_f32 v211, v20, v252, v227
	v_fma_f32 v253, -v21, v252, v253
	v_fmac_f32_e32 v211, v21, v251
	v_cndmask_b32_e64 v191, v24, v251, s[40:41]
	v_cndmask_b32_e64 v192, v25, v252, s[40:41]
	v_cndmask_b32_e64 v216, v53, v169, s[40:41]
	v_cndmask_b32_e64 v217, v85, v170, s[40:41]
	v_cndmask_b32_e64 v218, v169, v53, s[40:41]
	v_cndmask_b32_e64 v219, v170, v85, s[40:41]
	v_fma_f32 v249, v12, v215, v216
	v_fma_f32 v250, v12, v248, v217
	v_fma_f32 v249, -v13, v248, v249
	v_fmac_f32_e32 v250, v13, v215
	v_fma_f32 v213, v12, v249, v218
	v_fma_f32 v214, v12, v250, v219
	v_fma_f32 v213, -v13, v250, v213
	v_fmac_f32_e32 v214, v13, v249
	v_cndmask_b32_e64 v185, v215, v249, s[40:41]
	v_cndmask_b32_e64 v186, v248, v250, s[40:41]
	v_cndmask_b32_e64 v224, v69, v177, s[40:41]
	v_cndmask_b32_e64 v225, v101, v178, s[40:41]
	v_cndmask_b32_e64 v226, v177, v69, s[40:41]
	v_cndmask_b32_e64 v227, v178, v101, s[40:41]
	v_fma_f32 v212, v20, v253, v224
	v_fma_f32 v209, v20, v211, v225
	v_fma_f32 v212, -v21, v211, v212
	v_fmac_f32_e32 v209, v21, v253
	v_fma_f32 v251, v20, v212, v226
	v_fma_f32 v252, v20, v209, v227
	v_fma_f32 v251, -v21, v209, v251
	v_fmac_f32_e32 v252, v21, v212
	v_cndmask_b32_e64 v193, v253, v212, s[40:41]
	v_cndmask_b32_e64 v194, v211, v209, s[40:41]
	v_cndmask_b32_e64 v216, v57, v171, s[40:41]
	v_cndmask_b32_e64 v217, v89, v172, s[40:41]
	v_cndmask_b32_e64 v218, v171, v57, s[40:41]
	v_cndmask_b32_e64 v219, v172, v89, s[40:41]
	v_fma_f32 v215, v12, v213, v216
	v_fma_f32 v248, v12, v214, v217
	v_fma_f32 v215, -v13, v214, v215
	v_fmac_f32_e32 v248, v13, v213
	v_fma_f32 v249, v12, v215, v218
	v_fma_f32 v250, v12, v248, v219
	v_fma_f32 v249, -v13, v248, v249
	v_fmac_f32_e32 v250, v13, v215
	v_cndmask_b32_e64 v187, v213, v215, s[40:41]
	v_cndmask_b32_e64 v188, v214, v248, s[40:41]
	v_cndmask_b32_e64 v224, v73, v179, s[40:41]
	v_cndmask_b32_e64 v225, v105, v180, s[40:41]
	v_cndmask_b32_e64 v226, v179, v73, s[40:41]
	v_cndmask_b32_e64 v227, v180, v105, s[40:41]
	v_fma_f32 v253, v20, v251, v224
	v_fma_f32 v211, v20, v252, v225
	v_fma_f32 v253, -v21, v252, v253
	v_fmac_f32_e32 v211, v21, v251
	v_fma_f32 v212, v20, v253, v226
	v_fma_f32 v209, v20, v211, v227
	v_fma_f32 v212, -v21, v211, v212
	v_fmac_f32_e32 v209, v21, v253
	v_cndmask_b32_e64 v195, v251, v253, s[40:41]
	v_cndmask_b32_e64 v196, v252, v211, s[40:41]
	v_cndmask_b32_e64 v216, v61, v173, s[40:41]
	v_cndmask_b32_e64 v217, v93, v174, s[40:41]
	v_cndmask_b32_e64 v218, v173, v61, s[40:41]
	v_cndmask_b32_e64 v219, v174, v93, s[40:41]
	v_fma_f32 v213, v12, v249, v216
	v_fma_f32 v214, v12, v250, v217
	v_fma_f32 v213, -v13, v250, v213
	v_fmac_f32_e32 v214, v13, v249
	v_fma_f32 v215, v12, v213, v218
	v_fma_f32 v248, v12, v214, v219
	v_fma_f32 v215, -v13, v214, v215
	v_fmac_f32_e32 v248, v13, v213
	v_cndmask_b32_e64 v189, v249, v213, s[40:41]
	v_cndmask_b32_e64 v190, v250, v214, s[40:41]
	v_cndmask_b32_e64 v224, v77, v181, s[40:41]
	v_cndmask_b32_e64 v225, v109, v182, s[40:41]
	v_cndmask_b32_e64 v226, v181, v77, s[40:41]
	v_cndmask_b32_e64 v227, v182, v109, s[40:41]
	v_fma_f32 v251, v20, v212, v224
	v_fma_f32 v252, v20, v209, v225
	v_fma_f32 v251, -v21, v209, v251
	v_fmac_f32_e32 v252, v21, v212
	v_fma_f32 v253, v20, v251, v226
	v_fma_f32 v211, v20, v252, v227
	v_fma_f32 v253, -v21, v252, v253
	v_fmac_f32_e32 v211, v21, v251
	v_cndmask_b32_e64 v197, v212, v251, s[40:41]
	v_cndmask_b32_e64 v198, v209, v252, s[40:41]
	v_mov_b32_e32 v22, v215
	v_mov_b32_e32 v23, v248
	v_mov_b32_e32 v24, v253
	v_mov_b32_e32 v25, v211
	v_fmac_f32_e32 v46, v6, v183
	v_fmac_f32_e32 v78, v6, v184
	v_fma_f32 v46, -v7, v184, v46
	v_fmac_f32_e32 v78, v7, v183
	v_fmac_f32_e32 v47, v8, v183
	v_fmac_f32_e32 v79, v8, v184
	v_fma_f32 v47, -v9, v184, v47
	v_fmac_f32_e32 v79, v9, v183
	v_fmac_f32_e32 v48, v10, v183
	v_fmac_f32_e32 v80, v10, v184
	v_fma_f32 v48, -v11, v184, v48
	v_fmac_f32_e32 v80, v11, v183
	v_fmac_f32_e32 v49, v12, v183
	v_fmac_f32_e32 v81, v12, v184
	v_fma_f32 v49, -v13, v184, v49
	v_fmac_f32_e32 v81, v13, v183
	v_fmac_f32_e32 v50, v6, v185
	v_fmac_f32_e32 v82, v6, v186
	v_fma_f32 v50, -v7, v186, v50
	v_fmac_f32_e32 v82, v7, v185
	v_fmac_f32_e32 v51, v8, v185
	v_fmac_f32_e32 v83, v8, v186
	v_fma_f32 v51, -v9, v186, v51
	v_fmac_f32_e32 v83, v9, v185
	v_fmac_f32_e32 v52, v10, v185
	v_fmac_f32_e32 v84, v10, v186
	v_fma_f32 v52, -v11, v186, v52
	v_fmac_f32_e32 v84, v11, v185
	v_fmac_f32_e32 v53, v12, v185
	v_fmac_f32_e32 v85, v12, v186
	v_fma_f32 v53, -v13, v186, v53
	v_fmac_f32_e32 v85, v13, v185
	v_fmac_f32_e32 v54, v6, v187
	v_fmac_f32_e32 v86, v6, v188
	v_fma_f32 v54, -v7, v188, v54
	v_fmac_f32_e32 v86, v7, v187
	v_fmac_f32_e32 v55, v8, v187
	v_fmac_f32_e32 v87, v8, v188
	v_fma_f32 v55, -v9, v188, v55
	v_fmac_f32_e32 v87, v9, v187
	v_fmac_f32_e32 v56, v10, v187
	v_fmac_f32_e32 v88, v10, v188
	v_fma_f32 v56, -v11, v188, v56
	v_fmac_f32_e32 v88, v11, v187
	v_fmac_f32_e32 v57, v12, v187
	v_fmac_f32_e32 v89, v12, v188
	v_fma_f32 v57, -v13, v188, v57
	v_fmac_f32_e32 v89, v13, v187
	v_fmac_f32_e32 v58, v6, v189
	v_fmac_f32_e32 v90, v6, v190
	v_fma_f32 v58, -v7, v190, v58
	v_fmac_f32_e32 v90, v7, v189
	v_fmac_f32_e32 v59, v8, v189
	v_fmac_f32_e32 v91, v8, v190
	v_fma_f32 v59, -v9, v190, v59
	v_fmac_f32_e32 v91, v9, v189
	v_fmac_f32_e32 v60, v10, v189
	v_fmac_f32_e32 v92, v10, v190
	v_fma_f32 v60, -v11, v190, v60
	v_fmac_f32_e32 v92, v11, v189
	v_fmac_f32_e32 v61, v12, v189
	v_fmac_f32_e32 v93, v12, v190
	v_fma_f32 v61, -v13, v190, v61
	v_fmac_f32_e32 v93, v13, v189
	v_fmac_f32_e32 v62, v14, v191
	v_fmac_f32_e32 v94, v14, v192
	v_fma_f32 v62, -v15, v192, v62
	v_fmac_f32_e32 v94, v15, v191
	v_fmac_f32_e32 v63, v16, v191
	v_fmac_f32_e32 v95, v16, v192
	v_fma_f32 v63, -v17, v192, v63
	v_fmac_f32_e32 v95, v17, v191
	v_fmac_f32_e32 v64, v18, v191
	v_fmac_f32_e32 v96, v18, v192
	v_fma_f32 v64, -v19, v192, v64
	v_fmac_f32_e32 v96, v19, v191
	v_fmac_f32_e32 v65, v20, v191
	v_fmac_f32_e32 v97, v20, v192
	v_fma_f32 v65, -v21, v192, v65
	v_fmac_f32_e32 v97, v21, v191
	v_fmac_f32_e32 v66, v14, v193
	v_fmac_f32_e32 v98, v14, v194
	v_fma_f32 v66, -v15, v194, v66
	v_fmac_f32_e32 v98, v15, v193
	v_fmac_f32_e32 v67, v16, v193
	v_fmac_f32_e32 v99, v16, v194
	v_fma_f32 v67, -v17, v194, v67
	v_fmac_f32_e32 v99, v17, v193
	v_fmac_f32_e32 v68, v18, v193
	v_fmac_f32_e32 v100, v18, v194
	v_fma_f32 v68, -v19, v194, v68
	v_fmac_f32_e32 v100, v19, v193
	v_fmac_f32_e32 v69, v20, v193
	v_fmac_f32_e32 v101, v20, v194
	v_fma_f32 v69, -v21, v194, v69
	v_fmac_f32_e32 v101, v21, v193
	v_fmac_f32_e32 v70, v14, v195
	v_fmac_f32_e32 v102, v14, v196
	v_fma_f32 v70, -v15, v196, v70
	v_fmac_f32_e32 v102, v15, v195
	v_fmac_f32_e32 v71, v16, v195
	v_fmac_f32_e32 v103, v16, v196
	v_fma_f32 v71, -v17, v196, v71
	v_fmac_f32_e32 v103, v17, v195
	v_fmac_f32_e32 v72, v18, v195
	v_fmac_f32_e32 v104, v18, v196
	v_fma_f32 v72, -v19, v196, v72
	v_fmac_f32_e32 v104, v19, v195
	v_fmac_f32_e32 v73, v20, v195
	v_fmac_f32_e32 v105, v20, v196
	v_fma_f32 v73, -v21, v196, v73
	v_fmac_f32_e32 v105, v21, v195
	v_fmac_f32_e32 v74, v14, v197
	v_fmac_f32_e32 v106, v14, v198
	v_fma_f32 v74, -v15, v198, v74
	v_fmac_f32_e32 v106, v15, v197
	v_fmac_f32_e32 v75, v16, v197
	v_fmac_f32_e32 v107, v16, v198
	v_fma_f32 v75, -v17, v198, v75
	v_fmac_f32_e32 v107, v17, v197
	v_fmac_f32_e32 v76, v18, v197
	v_fmac_f32_e32 v108, v18, v198
	v_fma_f32 v76, -v19, v198, v76
	v_fmac_f32_e32 v108, v19, v197
	v_fmac_f32_e32 v77, v20, v197
	v_fmac_f32_e32 v109, v20, v198
	v_fma_f32 v77, -v21, v198, v77
	v_fmac_f32_e32 v109, v21, v197
	v_cvt_pk_bf16_f32 v216, v46, v47
	v_cvt_pk_bf16_f32 v217, v48, v49
	ds_write_b64 v200, v[216:217] offset:0
	v_cvt_pk_bf16_f32 v218, v50, v51
	v_cvt_pk_bf16_f32 v219, v52, v53
	ds_write_b64 v200, v[218:219] offset:16
	v_cvt_pk_bf16_f32 v220, v54, v55
	v_cvt_pk_bf16_f32 v221, v56, v57
	ds_write_b64 v200, v[220:221] offset:32
	v_cvt_pk_bf16_f32 v222, v58, v59
	v_cvt_pk_bf16_f32 v223, v60, v61
	ds_write_b64 v200, v[222:223] offset:48
	v_cvt_pk_bf16_f32 v224, v62, v63
	v_cvt_pk_bf16_f32 v225, v64, v65
	ds_write_b64 v200, v[224:225] offset:2048
	v_cvt_pk_bf16_f32 v226, v66, v67
	v_cvt_pk_bf16_f32 v227, v68, v69
	ds_write_b64 v200, v[226:227] offset:2064
	v_cvt_pk_bf16_f32 v228, v70, v71
	v_cvt_pk_bf16_f32 v229, v72, v73
	ds_write_b64 v200, v[228:229] offset:2080
	v_cvt_pk_bf16_f32 v230, v74, v75
	v_cvt_pk_bf16_f32 v231, v76, v77
	ds_write_b64 v200, v[230:231] offset:2096
	v_cvt_pk_bf16_f32 v232, v78, v79
	v_cvt_pk_bf16_f32 v233, v80, v81
	ds_write_b64 v200, v[232:233] offset:4096
	v_cvt_pk_bf16_f32 v234, v82, v83
	v_cvt_pk_bf16_f32 v235, v84, v85
	ds_write_b64 v200, v[234:235] offset:4112
	v_cvt_pk_bf16_f32 v236, v86, v87
	v_cvt_pk_bf16_f32 v237, v88, v89
	ds_write_b64 v200, v[236:237] offset:4128
	v_cvt_pk_bf16_f32 v238, v90, v91
	v_cvt_pk_bf16_f32 v239, v92, v93
	ds_write_b64 v200, v[238:239] offset:4144
	v_cvt_pk_bf16_f32 v240, v94, v95
	v_cvt_pk_bf16_f32 v241, v96, v97
	ds_write_b64 v200, v[240:241] offset:6144
	v_cvt_pk_bf16_f32 v242, v98, v99
	v_cvt_pk_bf16_f32 v243, v100, v101
	ds_write_b64 v200, v[242:243] offset:6160
	v_cvt_pk_bf16_f32 v244, v102, v103
	v_cvt_pk_bf16_f32 v245, v104, v105
	ds_write_b64 v200, v[244:245] offset:6176
	v_cvt_pk_bf16_f32 v246, v106, v107
	v_cvt_pk_bf16_f32 v247, v108, v109
	ds_write_b64 v200, v[246:247] offset:6192
	s_waitcnt lgkmcnt(0)
	ds_read_b64_tr_b16 v[216:217], v201 offset:0
	ds_read_b64_tr_b16 v[218:219], v201 offset:256
	ds_read_b64_tr_b16 v[220:221], v201 offset:1024
	ds_read_b64_tr_b16 v[222:223], v201 offset:1280
	ds_read_b64_tr_b16 v[224:225], v201 offset:2048
	ds_read_b64_tr_b16 v[226:227], v201 offset:2304
	ds_read_b64_tr_b16 v[228:229], v201 offset:3072
	ds_read_b64_tr_b16 v[230:231], v201 offset:3328
	ds_read_b64_tr_b16 v[232:233], v201 offset:4096
	ds_read_b64_tr_b16 v[234:235], v201 offset:4352
	ds_read_b64_tr_b16 v[236:237], v201 offset:5120
	ds_read_b64_tr_b16 v[238:239], v201 offset:5376
	ds_read_b64_tr_b16 v[240:241], v201 offset:6144
	ds_read_b64_tr_b16 v[242:243], v201 offset:6400
	ds_read_b64_tr_b16 v[244:245], v201 offset:7168
	ds_read_b64_tr_b16 v[246:247], v201 offset:7424
	s_waitcnt lgkmcnt(14)
	v_mfma_f32_32x32x16_bf16 v[110:125], v[216:219], v[134:137], v[110:125]
	s_waitcnt lgkmcnt(12)
	v_mfma_f32_32x32x16_bf16 v[110:125], v[220:223], v[138:141], v[110:125]
	s_waitcnt lgkmcnt(10)
	v_mfma_f32_32x32x16_bf16 v[110:125], v[224:227], v[142:145], v[110:125]
	s_waitcnt lgkmcnt(8)
	v_mfma_f32_32x32x16_bf16 v[110:125], v[228:231], v[146:149], v[110:125]
	s_waitcnt lgkmcnt(6)
	v_mfma_f32_32x32x16_bf16 v[110:125], v[232:235], v[150:153], v[110:125]
	s_waitcnt lgkmcnt(4)
	v_mfma_f32_32x32x16_bf16 v[110:125], v[236:239], v[154:157], v[110:125]
	s_waitcnt lgkmcnt(2)
	v_mfma_f32_32x32x16_bf16 v[110:125], v[240:243], v[158:161], v[110:125]
	s_waitcnt lgkmcnt(0)
	v_mfma_f32_32x32x16_bf16 v[110:125], v[244:247], v[162:165], v[110:125]
	s_nop 7
	s_nop 3
	s_mov_b64 exec, s[44:45]
	ds_write_b32 v202, v110 offset:0
	ds_write_b32 v202, v111 offset:64
	ds_write_b32 v202, v112 offset:128
	ds_write_b32 v202, v113 offset:192
	ds_write_b32 v202, v114 offset:512
	ds_write_b32 v202, v115 offset:576
	ds_write_b32 v202, v116 offset:640
	ds_write_b32 v202, v117 offset:704
	ds_write_b32 v202, v118 offset:1024
	ds_write_b32 v202, v119 offset:1088
	ds_write_b32 v202, v120 offset:1152
	ds_write_b32 v202, v121 offset:1216
	ds_write_b32 v202, v122 offset:1536
	ds_write_b32 v202, v123 offset:1600
	ds_write_b32 v202, v124 offset:1664
	ds_write_b32 v202, v125 offset:1728
	s_mov_b64 exec, -1
	s_waitcnt lgkmcnt(0)
	ds_read_b128 v[216:219], v203
	ds_read_b128 v[220:223], v203 offset:16
	s_waitcnt lgkmcnt(0)
	v_mul_f32_e32 v224, 0x3d372713, v216
	v_mul_f32_e32 v225, 0x3d372713, v217
	v_mul_f32_e32 v226, 0x3d372713, v218
	v_mul_f32_e32 v227, 0x3d372713, v219
	v_mul_f32_e32 v228, 0x3d372713, v220
	v_mul_f32_e32 v229, 0x3d372713, v221
	v_mul_f32_e32 v230, 0x3d372713, v222
	v_mul_f32_e32 v231, 0x3d372713, v223
	v_mul_f32_e32 v224, v216, v224
	v_mul_f32_e32 v225, v217, v225
	v_mul_f32_e32 v226, v218, v226
	v_mul_f32_e32 v227, v219, v227
	v_mul_f32_e32 v228, v220, v228
	v_mul_f32_e32 v229, v221, v229
	v_mul_f32_e32 v230, v222, v230
	v_mul_f32_e32 v231, v223, v231
	v_fma_f32 v224, v216, v224, v216
	v_fma_f32 v225, v217, v225, v217
	v_fma_f32 v226, v218, v226, v218
	v_fma_f32 v227, v219, v227, v219
	v_fma_f32 v228, v220, v228, v220
	v_fma_f32 v229, v221, v229, v221
	v_fma_f32 v230, v222, v230, v222
	v_fma_f32 v231, v223, v231, v223
	v_mul_f32_e32 v224, 0x3f4c422a, v224
	v_mul_f32_e32 v225, 0x3f4c422a, v225
	v_mul_f32_e32 v226, 0x3f4c422a, v226
	v_mul_f32_e32 v227, 0x3f4c422a, v227
	v_mul_f32_e32 v228, 0x3f4c422a, v228
	v_mul_f32_e32 v229, 0x3f4c422a, v229
	v_mul_f32_e32 v230, 0x3f4c422a, v230
	v_mul_f32_e32 v231, 0x3f4c422a, v231
	v_add_f32_e32 v224, v224, v224
	v_add_f32_e32 v225, v225, v225
	v_add_f32_e32 v226, v226, v226
	v_add_f32_e32 v227, v227, v227
	v_add_f32_e32 v228, v228, v228
	v_add_f32_e32 v229, v229, v229
	v_add_f32_e32 v230, v230, v230
	v_add_f32_e32 v231, v231, v231
	v_mul_f32_e32 v224, 0xbfb8aa3b, v224
	v_mul_f32_e32 v225, 0xbfb8aa3b, v225
	v_mul_f32_e32 v226, 0xbfb8aa3b, v226
	v_mul_f32_e32 v227, 0xbfb8aa3b, v227
	v_mul_f32_e32 v228, 0xbfb8aa3b, v228
	v_mul_f32_e32 v229, 0xbfb8aa3b, v229
	v_mul_f32_e32 v230, 0xbfb8aa3b, v230
	v_mul_f32_e32 v231, 0xbfb8aa3b, v231
	v_exp_f32_e32 v224, v224
	v_exp_f32_e32 v225, v225
	v_exp_f32_e32 v226, v226
	v_exp_f32_e32 v227, v227
	v_exp_f32_e32 v228, v228
	v_exp_f32_e32 v229, v229
	v_exp_f32_e32 v230, v230
	v_exp_f32_e32 v231, v231
	s_nop 0
	v_add_f32_e32 v224, 1.0, v224
	v_add_f32_e32 v225, 1.0, v225
	v_add_f32_e32 v226, 1.0, v226
	v_add_f32_e32 v227, 1.0, v227
	v_add_f32_e32 v228, 1.0, v228
	v_add_f32_e32 v229, 1.0, v229
	v_add_f32_e32 v230, 1.0, v230
	v_add_f32_e32 v231, 1.0, v231
	v_rcp_f32_e32 v224, v224
	v_rcp_f32_e32 v225, v225
	v_rcp_f32_e32 v226, v226
	v_rcp_f32_e32 v227, v227
	v_rcp_f32_e32 v228, v228
	v_rcp_f32_e32 v229, v229
	v_rcp_f32_e32 v230, v230
	v_rcp_f32_e32 v231, v231
	s_nop 0
	v_mul_f32_e32 v224, v216, v224
	v_mul_f32_e32 v225, v217, v225
	v_mul_f32_e32 v226, v218, v226
	v_mul_f32_e32 v227, v219, v227
	v_mul_f32_e32 v228, v220, v228
	v_mul_f32_e32 v229, v221, v229
	v_mul_f32_e32 v230, v222, v230
	v_mul_f32_e32 v231, v223, v231
	v_cvt_pk_bf16_f32 v232, v224, v225
	v_cvt_pk_bf16_f32 v233, v226, v227
	v_cvt_pk_bf16_f32 v234, v228, v229
	v_cvt_pk_bf16_f32 v235, v230, v231
	s_add_u32 s70, s60, 0x0
	s_addc_u32 s71, s61, 0
	global_store_dwordx4 v205, v[232:235], s[70:71]
	s_waitcnt vmcnt(1)
	v_mfma_f32_32x32x16_bf16 v[46:61], v[130:133], v[26:29], 0
	v_mfma_f32_32x32x16_bf16 v[78:93], v[130:133], v[34:37], 0
	v_mfma_f32_32x32x16_bf16 v[62:77], v[130:133], v[30:33], 0
	v_mfma_f32_32x32x16_bf16 v[94:109], v[130:133], v[38:41], 0
	v_mfma_f32_32x32x16_bf16 v[110:125], v[130:133], v[42:45], 0
	s_add_u32 s70, s58, 0x40000
	s_addc_u32 s71, s59, 0
	global_load_dwordx4 v[126:129], v204, s[70:71]
	s_nop 7
	s_nop 1
	v_fmac_f32_e32 v47, v6, v46
	v_fmac_f32_e32 v79, v6, v78
	v_fma_f32 v47, -v7, v78, v47
	v_fmac_f32_e32 v79, v7, v46
	v_fmac_f32_e32 v51, v6, v50
	v_fmac_f32_e32 v83, v6, v82
	v_fma_f32 v51, -v7, v82, v51
	v_fmac_f32_e32 v83, v7, v50
	v_fmac_f32_e32 v55, v6, v54
	v_fmac_f32_e32 v87, v6, v86
	v_fma_f32 v55, -v7, v86, v55
	v_fmac_f32_e32 v87, v7, v54
	v_fmac_f32_e32 v59, v6, v58
	v_fmac_f32_e32 v91, v6, v90
	v_fma_f32 v59, -v7, v90, v59
	v_fmac_f32_e32 v91, v7, v58
	v_fmac_f32_e32 v63, v14, v62
	v_fmac_f32_e32 v95, v14, v94
	v_fma_f32 v63, -v15, v94, v63
	v_fmac_f32_e32 v95, v15, v62
	v_fmac_f32_e32 v67, v14, v66
	v_fmac_f32_e32 v99, v14, v98
	v_fma_f32 v67, -v15, v98, v67
	v_fmac_f32_e32 v99, v15, v66
	v_fmac_f32_e32 v71, v14, v70
	v_fmac_f32_e32 v103, v14, v102
	v_fma_f32 v71, -v15, v102, v71
	v_fmac_f32_e32 v103, v15, v70
	v_fmac_f32_e32 v75, v14, v74
	v_fmac_f32_e32 v107, v14, v106
	v_fma_f32 v75, -v15, v106, v75
	v_fmac_f32_e32 v107, v15, v74
	v_fmac_f32_e32 v48, v6, v47
	v_fmac_f32_e32 v80, v6, v79
	v_fma_f32 v48, -v7, v79, v48
	v_fmac_f32_e32 v80, v7, v47
	v_fmac_f32_e32 v52, v6, v51
	v_fmac_f32_e32 v84, v6, v83
	v_fma_f32 v52, -v7, v83, v52
	v_fmac_f32_e32 v84, v7, v51
	v_fmac_f32_e32 v56, v6, v55
	v_fmac_f32_e32 v88, v6, v87
	v_fma_f32 v56, -v7, v87, v56
	v_fmac_f32_e32 v88, v7, v55
	v_fmac_f32_e32 v60, v6, v59
	v_fmac_f32_e32 v92, v6, v91
	v_fma_f32 v60, -v7, v91, v60
	v_fmac_f32_e32 v92, v7, v59
	v_fmac_f32_e32 v64, v14, v63
	v_fmac_f32_e32 v96, v14, v95
	v_fma_f32 v64, -v15, v95, v64
	v_fmac_f32_e32 v96, v15, v63
	v_fmac_f32_e32 v68, v14, v67
	v_fmac_f32_e32 v100, v14, v99
	v_fma_f32 v68, -v15, v99, v68
	v_fmac_f32_e32 v100, v15, v67
	v_fmac_f32_e32 v72, v14, v71
	v_fmac_f32_e32 v104, v14, v103
	v_fma_f32 v72, -v15, v103, v72
	v_fmac_f32_e32 v104, v15, v71
	v_fmac_f32_e32 v76, v14, v75
	v_fmac_f32_e32 v108, v14, v107
	v_fma_f32 v76, -v15, v107, v76
	v_fmac_f32_e32 v108, v15, v75
	v_fmac_f32_e32 v49, v6, v48
	v_fmac_f32_e32 v81, v6, v80
	v_fma_f32 v49, -v7, v80, v49
	v_fmac_f32_e32 v81, v7, v48
	v_fmac_f32_e32 v53, v6, v52
	v_fmac_f32_e32 v85, v6, v84
	v_fma_f32 v53, -v7, v84, v53
	v_fmac_f32_e32 v85, v7, v52
	v_fmac_f32_e32 v57, v6, v56
	v_fmac_f32_e32 v89, v6, v88
	v_fma_f32 v57, -v7, v88, v57
	v_fmac_f32_e32 v89, v7, v56
	v_fmac_f32_e32 v61, v6, v60
	v_fmac_f32_e32 v93, v6, v92
	v_fma_f32 v61, -v7, v92, v61
	v_fmac_f32_e32 v93, v7, v60
	v_fmac_f32_e32 v65, v14, v64
	v_fmac_f32_e32 v97, v14, v96
	v_fma_f32 v65, -v15, v96, v65
	v_fmac_f32_e32 v97, v15, v64
	v_fmac_f32_e32 v69, v14, v68
	v_fmac_f32_e32 v101, v14, v100
	v_fma_f32 v69, -v15, v100, v69
	v_fmac_f32_e32 v101, v15, v68
	v_fmac_f32_e32 v73, v14, v72
	v_fmac_f32_e32 v105, v14, v104
	v_fma_f32 v73, -v15, v104, v73
	v_fmac_f32_e32 v105, v15, v72
	v_fmac_f32_e32 v77, v14, v76
	v_fmac_f32_e32 v109, v14, v108
	v_fma_f32 v77, -v15, v108, v77
	v_fmac_f32_e32 v109, v15, v76
	ds_bpermute_b32 v167, v199, v49
	ds_bpermute_b32 v168, v199, v81
	ds_bpermute_b32 v169, v199, v53
	ds_bpermute_b32 v170, v199, v85
	ds_bpermute_b32 v171, v199, v57
	ds_bpermute_b32 v172, v199, v89
	ds_bpermute_b32 v173, v199, v61
	ds_bpermute_b32 v174, v199, v93
	ds_bpermute_b32 v175, v199, v65
	ds_bpermute_b32 v176, v199, v97
	ds_bpermute_b32 v177, v199, v69
	ds_bpermute_b32 v178, v199, v101
	ds_bpermute_b32 v179, v199, v73
	ds_bpermute_b32 v180, v199, v105
	ds_bpermute_b32 v181, v199, v77
	ds_bpermute_b32 v182, v199, v109
	s_waitcnt lgkmcnt(0)
	v_cndmask_b32_e64 v216, v49, v167, s[40:41]
	v_cndmask_b32_e64 v217, v81, v168, s[40:41]
	v_cndmask_b32_e64 v218, v167, v49, s[40:41]
	v_cndmask_b32_e64 v219, v168, v81, s[40:41]
	v_fma_f32 v213, v12, v22, v216
	v_fma_f32 v214, v12, v23, v217
	v_fma_f32 v213, -v13, v23, v213
	v_fmac_f32_e32 v214, v13, v22
	v_fma_f32 v215, v12, v213, v218
	v_fma_f32 v248, v12, v214, v219
	v_fma_f32 v215, -v13, v214, v215
	v_fmac_f32_e32 v248, v13, v213
	v_cndmask_b32_e64 v183, v22, v213, s[40:41]
	v_cndmask_b32_e64 v184, v23, v214, s[40:41]
	v_cndmask_b32_e64 v224, v65, v175, s[40:41]
	v_cndmask_b32_e64 v225, v97, v176, s[40:41]
	v_cndmask_b32_e64 v226, v175, v65, s[40:41]
	v_cndmask_b32_e64 v227, v176, v97, s[40:41]
	v_fma_f32 v251, v20, v24, v224
	v_fma_f32 v252, v20, v25, v225
	v_fma_f32 v251, -v21, v25, v251
	v_fmac_f32_e32 v252, v21, v24
	v_fma_f32 v253, v20, v251, v226
	v_fma_f32 v211, v20, v252, v227
	v_fma_f32 v253, -v21, v252, v253
	v_fmac_f32_e32 v211, v21, v251
	v_cndmask_b32_e64 v191, v24, v251, s[40:41]
	v_cndmask_b32_e64 v192, v25, v252, s[40:41]
	v_cndmask_b32_e64 v216, v53, v169, s[40:41]
	v_cndmask_b32_e64 v217, v85, v170, s[40:41]
	v_cndmask_b32_e64 v218, v169, v53, s[40:41]
	v_cndmask_b32_e64 v219, v170, v85, s[40:41]
	v_fma_f32 v249, v12, v215, v216
	v_fma_f32 v250, v12, v248, v217
	v_fma_f32 v249, -v13, v248, v249
	v_fmac_f32_e32 v250, v13, v215
	v_fma_f32 v213, v12, v249, v218
	v_fma_f32 v214, v12, v250, v219
	v_fma_f32 v213, -v13, v250, v213
	v_fmac_f32_e32 v214, v13, v249
	v_cndmask_b32_e64 v185, v215, v249, s[40:41]
	v_cndmask_b32_e64 v186, v248, v250, s[40:41]
	v_cndmask_b32_e64 v224, v69, v177, s[40:41]
	v_cndmask_b32_e64 v225, v101, v178, s[40:41]
	v_cndmask_b32_e64 v226, v177, v69, s[40:41]
	v_cndmask_b32_e64 v227, v178, v101, s[40:41]
	v_fma_f32 v212, v20, v253, v224
	v_fma_f32 v209, v20, v211, v225
	v_fma_f32 v212, -v21, v211, v212
	v_fmac_f32_e32 v209, v21, v253
	v_fma_f32 v251, v20, v212, v226
	v_fma_f32 v252, v20, v209, v227
	v_fma_f32 v251, -v21, v209, v251
	v_fmac_f32_e32 v252, v21, v212
	v_cndmask_b32_e64 v193, v253, v212, s[40:41]
	v_cndmask_b32_e64 v194, v211, v209, s[40:41]
	v_cndmask_b32_e64 v216, v57, v171, s[40:41]
	v_cndmask_b32_e64 v217, v89, v172, s[40:41]
	v_cndmask_b32_e64 v218, v171, v57, s[40:41]
	v_cndmask_b32_e64 v219, v172, v89, s[40:41]
	v_fma_f32 v215, v12, v213, v216
	v_fma_f32 v248, v12, v214, v217
	v_fma_f32 v215, -v13, v214, v215
	v_fmac_f32_e32 v248, v13, v213
	v_fma_f32 v249, v12, v215, v218
	v_fma_f32 v250, v12, v248, v219
	v_fma_f32 v249, -v13, v248, v249
	v_fmac_f32_e32 v250, v13, v215
	v_cndmask_b32_e64 v187, v213, v215, s[40:41]
	v_cndmask_b32_e64 v188, v214, v248, s[40:41]
	v_cndmask_b32_e64 v224, v73, v179, s[40:41]
	v_cndmask_b32_e64 v225, v105, v180, s[40:41]
	v_cndmask_b32_e64 v226, v179, v73, s[40:41]
	v_cndmask_b32_e64 v227, v180, v105, s[40:41]
	v_fma_f32 v253, v20, v251, v224
	v_fma_f32 v211, v20, v252, v225
	v_fma_f32 v253, -v21, v252, v253
	v_fmac_f32_e32 v211, v21, v251
	v_fma_f32 v212, v20, v253, v226
	v_fma_f32 v209, v20, v211, v227
	v_fma_f32 v212, -v21, v211, v212
	v_fmac_f32_e32 v209, v21, v253
	v_cndmask_b32_e64 v195, v251, v253, s[40:41]
	v_cndmask_b32_e64 v196, v252, v211, s[40:41]
	v_cndmask_b32_e64 v216, v61, v173, s[40:41]
	v_cndmask_b32_e64 v217, v93, v174, s[40:41]
	v_cndmask_b32_e64 v218, v173, v61, s[40:41]
	v_cndmask_b32_e64 v219, v174, v93, s[40:41]
	v_fma_f32 v213, v12, v249, v216
	v_fma_f32 v214, v12, v250, v217
	v_fma_f32 v213, -v13, v250, v213
	v_fmac_f32_e32 v214, v13, v249
	v_fma_f32 v215, v12, v213, v218
	v_fma_f32 v248, v12, v214, v219
	v_fma_f32 v215, -v13, v214, v215
	v_fmac_f32_e32 v248, v13, v213
	v_cndmask_b32_e64 v189, v249, v213, s[40:41]
	v_cndmask_b32_e64 v190, v250, v214, s[40:41]
	v_cndmask_b32_e64 v224, v77, v181, s[40:41]
	v_cndmask_b32_e64 v225, v109, v182, s[40:41]
	v_cndmask_b32_e64 v226, v181, v77, s[40:41]
	v_cndmask_b32_e64 v227, v182, v109, s[40:41]
	v_fma_f32 v251, v20, v212, v224
	v_fma_f32 v252, v20, v209, v225
	v_fma_f32 v251, -v21, v209, v251
	v_fmac_f32_e32 v252, v21, v212
	v_fma_f32 v253, v20, v251, v226
	v_fma_f32 v211, v20, v252, v227
	v_fma_f32 v253, -v21, v252, v253
	v_fmac_f32_e32 v211, v21, v251
	v_cndmask_b32_e64 v197, v212, v251, s[40:41]
	v_cndmask_b32_e64 v198, v209, v252, s[40:41]
	v_mov_b32_e32 v22, v215
	v_mov_b32_e32 v23, v248
	v_mov_b32_e32 v24, v253
	v_mov_b32_e32 v25, v211
	v_fmac_f32_e32 v46, v6, v183
	v_fmac_f32_e32 v78, v6, v184
	v_fma_f32 v46, -v7, v184, v46
	v_fmac_f32_e32 v78, v7, v183
	v_fmac_f32_e32 v47, v8, v183
	v_fmac_f32_e32 v79, v8, v184
	v_fma_f32 v47, -v9, v184, v47
	v_fmac_f32_e32 v79, v9, v183
	v_fmac_f32_e32 v48, v10, v183
	v_fmac_f32_e32 v80, v10, v184
	v_fma_f32 v48, -v11, v184, v48
	v_fmac_f32_e32 v80, v11, v183
	v_fmac_f32_e32 v49, v12, v183
	v_fmac_f32_e32 v81, v12, v184
	v_fma_f32 v49, -v13, v184, v49
	v_fmac_f32_e32 v81, v13, v183
	v_fmac_f32_e32 v50, v6, v185
	v_fmac_f32_e32 v82, v6, v186
	v_fma_f32 v50, -v7, v186, v50
	v_fmac_f32_e32 v82, v7, v185
	v_fmac_f32_e32 v51, v8, v185
	v_fmac_f32_e32 v83, v8, v186
	v_fma_f32 v51, -v9, v186, v51
	v_fmac_f32_e32 v83, v9, v185
	v_fmac_f32_e32 v52, v10, v185
	v_fmac_f32_e32 v84, v10, v186
	v_fma_f32 v52, -v11, v186, v52
	v_fmac_f32_e32 v84, v11, v185
	v_fmac_f32_e32 v53, v12, v185
	v_fmac_f32_e32 v85, v12, v186
	v_fma_f32 v53, -v13, v186, v53
	v_fmac_f32_e32 v85, v13, v185
	v_fmac_f32_e32 v54, v6, v187
	v_fmac_f32_e32 v86, v6, v188
	v_fma_f32 v54, -v7, v188, v54
	v_fmac_f32_e32 v86, v7, v187
	v_fmac_f32_e32 v55, v8, v187
	v_fmac_f32_e32 v87, v8, v188
	v_fma_f32 v55, -v9, v188, v55
	v_fmac_f32_e32 v87, v9, v187
	v_fmac_f32_e32 v56, v10, v187
	v_fmac_f32_e32 v88, v10, v188
	v_fma_f32 v56, -v11, v188, v56
	v_fmac_f32_e32 v88, v11, v187
	v_fmac_f32_e32 v57, v12, v187
	v_fmac_f32_e32 v89, v12, v188
	v_fma_f32 v57, -v13, v188, v57
	v_fmac_f32_e32 v89, v13, v187
	v_fmac_f32_e32 v58, v6, v189
	v_fmac_f32_e32 v90, v6, v190
	v_fma_f32 v58, -v7, v190, v58
	v_fmac_f32_e32 v90, v7, v189
	v_fmac_f32_e32 v59, v8, v189
	v_fmac_f32_e32 v91, v8, v190
	v_fma_f32 v59, -v9, v190, v59
	v_fmac_f32_e32 v91, v9, v189
	v_fmac_f32_e32 v60, v10, v189
	v_fmac_f32_e32 v92, v10, v190
	v_fma_f32 v60, -v11, v190, v60
	v_fmac_f32_e32 v92, v11, v189
	v_fmac_f32_e32 v61, v12, v189
	v_fmac_f32_e32 v93, v12, v190
	v_fma_f32 v61, -v13, v190, v61
	v_fmac_f32_e32 v93, v13, v189
	v_fmac_f32_e32 v62, v14, v191
	v_fmac_f32_e32 v94, v14, v192
	v_fma_f32 v62, -v15, v192, v62
	v_fmac_f32_e32 v94, v15, v191
	v_fmac_f32_e32 v63, v16, v191
	v_fmac_f32_e32 v95, v16, v192
	v_fma_f32 v63, -v17, v192, v63
	v_fmac_f32_e32 v95, v17, v191
	v_fmac_f32_e32 v64, v18, v191
	v_fmac_f32_e32 v96, v18, v192
	v_fma_f32 v64, -v19, v192, v64
	v_fmac_f32_e32 v96, v19, v191
	v_fmac_f32_e32 v65, v20, v191
	v_fmac_f32_e32 v97, v20, v192
	v_fma_f32 v65, -v21, v192, v65
	v_fmac_f32_e32 v97, v21, v191
	v_fmac_f32_e32 v66, v14, v193
	v_fmac_f32_e32 v98, v14, v194
	v_fma_f32 v66, -v15, v194, v66
	v_fmac_f32_e32 v98, v15, v193
	v_fmac_f32_e32 v67, v16, v193
	v_fmac_f32_e32 v99, v16, v194
	v_fma_f32 v67, -v17, v194, v67
	v_fmac_f32_e32 v99, v17, v193
	v_fmac_f32_e32 v68, v18, v193
	v_fmac_f32_e32 v100, v18, v194
	v_fma_f32 v68, -v19, v194, v68
	v_fmac_f32_e32 v100, v19, v193
	v_fmac_f32_e32 v69, v20, v193
	v_fmac_f32_e32 v101, v20, v194
	v_fma_f32 v69, -v21, v194, v69
	v_fmac_f32_e32 v101, v21, v193
	v_fmac_f32_e32 v70, v14, v195
	v_fmac_f32_e32 v102, v14, v196
	v_fma_f32 v70, -v15, v196, v70
	v_fmac_f32_e32 v102, v15, v195
	v_fmac_f32_e32 v71, v16, v195
	v_fmac_f32_e32 v103, v16, v196
	v_fma_f32 v71, -v17, v196, v71
	v_fmac_f32_e32 v103, v17, v195
	v_fmac_f32_e32 v72, v18, v195
	v_fmac_f32_e32 v104, v18, v196
	v_fma_f32 v72, -v19, v196, v72
	v_fmac_f32_e32 v104, v19, v195
	v_fmac_f32_e32 v73, v20, v195
	v_fmac_f32_e32 v105, v20, v196
	v_fma_f32 v73, -v21, v196, v73
	v_fmac_f32_e32 v105, v21, v195
	v_fmac_f32_e32 v74, v14, v197
	v_fmac_f32_e32 v106, v14, v198
	v_fma_f32 v74, -v15, v198, v74
	v_fmac_f32_e32 v106, v15, v197
	v_fmac_f32_e32 v75, v16, v197
	v_fmac_f32_e32 v107, v16, v198
	v_fma_f32 v75, -v17, v198, v75
	v_fmac_f32_e32 v107, v17, v197
	v_fmac_f32_e32 v76, v18, v197
	v_fmac_f32_e32 v108, v18, v198
	v_fma_f32 v76, -v19, v198, v76
	v_fmac_f32_e32 v108, v19, v197
	v_fmac_f32_e32 v77, v20, v197
	v_fmac_f32_e32 v109, v20, v198
	v_fma_f32 v77, -v21, v198, v77
	v_fmac_f32_e32 v109, v21, v197
	v_cvt_pk_bf16_f32 v216, v46, v47
	v_cvt_pk_bf16_f32 v217, v48, v49
	ds_write_b64 v200, v[216:217] offset:0
	v_cvt_pk_bf16_f32 v218, v50, v51
	v_cvt_pk_bf16_f32 v219, v52, v53
	ds_write_b64 v200, v[218:219] offset:16
	v_cvt_pk_bf16_f32 v220, v54, v55
	v_cvt_pk_bf16_f32 v221, v56, v57
	ds_write_b64 v200, v[220:221] offset:32
	v_cvt_pk_bf16_f32 v222, v58, v59
	v_cvt_pk_bf16_f32 v223, v60, v61
	ds_write_b64 v200, v[222:223] offset:48
	v_cvt_pk_bf16_f32 v224, v62, v63
	v_cvt_pk_bf16_f32 v225, v64, v65
	ds_write_b64 v200, v[224:225] offset:2048
	v_cvt_pk_bf16_f32 v226, v66, v67
	v_cvt_pk_bf16_f32 v227, v68, v69
	ds_write_b64 v200, v[226:227] offset:2064
	v_cvt_pk_bf16_f32 v228, v70, v71
	v_cvt_pk_bf16_f32 v229, v72, v73
	ds_write_b64 v200, v[228:229] offset:2080
	v_cvt_pk_bf16_f32 v230, v74, v75
	v_cvt_pk_bf16_f32 v231, v76, v77
	ds_write_b64 v200, v[230:231] offset:2096
	v_cvt_pk_bf16_f32 v232, v78, v79
	v_cvt_pk_bf16_f32 v233, v80, v81
	ds_write_b64 v200, v[232:233] offset:4096
	v_cvt_pk_bf16_f32 v234, v82, v83
	v_cvt_pk_bf16_f32 v235, v84, v85
	ds_write_b64 v200, v[234:235] offset:4112
	v_cvt_pk_bf16_f32 v236, v86, v87
	v_cvt_pk_bf16_f32 v237, v88, v89
	ds_write_b64 v200, v[236:237] offset:4128
	v_cvt_pk_bf16_f32 v238, v90, v91
	v_cvt_pk_bf16_f32 v239, v92, v93
	ds_write_b64 v200, v[238:239] offset:4144
	v_cvt_pk_bf16_f32 v240, v94, v95
	v_cvt_pk_bf16_f32 v241, v96, v97
	ds_write_b64 v200, v[240:241] offset:6144
	v_cvt_pk_bf16_f32 v242, v98, v99
	v_cvt_pk_bf16_f32 v243, v100, v101
	ds_write_b64 v200, v[242:243] offset:6160
	v_cvt_pk_bf16_f32 v244, v102, v103
	v_cvt_pk_bf16_f32 v245, v104, v105
	ds_write_b64 v200, v[244:245] offset:6176
	v_cvt_pk_bf16_f32 v246, v106, v107
	v_cvt_pk_bf16_f32 v247, v108, v109
	ds_write_b64 v200, v[246:247] offset:6192
	s_waitcnt lgkmcnt(0)
	ds_read_b64_tr_b16 v[216:217], v201 offset:0
	ds_read_b64_tr_b16 v[218:219], v201 offset:256
	ds_read_b64_tr_b16 v[220:221], v201 offset:1024
	ds_read_b64_tr_b16 v[222:223], v201 offset:1280
	ds_read_b64_tr_b16 v[224:225], v201 offset:2048
	ds_read_b64_tr_b16 v[226:227], v201 offset:2304
	ds_read_b64_tr_b16 v[228:229], v201 offset:3072
	ds_read_b64_tr_b16 v[230:231], v201 offset:3328
	ds_read_b64_tr_b16 v[232:233], v201 offset:4096
	ds_read_b64_tr_b16 v[234:235], v201 offset:4352
	ds_read_b64_tr_b16 v[236:237], v201 offset:5120
	ds_read_b64_tr_b16 v[238:239], v201 offset:5376
	ds_read_b64_tr_b16 v[240:241], v201 offset:6144
	ds_read_b64_tr_b16 v[242:243], v201 offset:6400
	ds_read_b64_tr_b16 v[244:245], v201 offset:7168
	ds_read_b64_tr_b16 v[246:247], v201 offset:7424
	s_waitcnt lgkmcnt(14)
	v_mfma_f32_32x32x16_bf16 v[110:125], v[216:219], v[134:137], v[110:125]
	s_waitcnt lgkmcnt(12)
	v_mfma_f32_32x32x16_bf16 v[110:125], v[220:223], v[138:141], v[110:125]
	s_waitcnt lgkmcnt(10)
	v_mfma_f32_32x32x16_bf16 v[110:125], v[224:227], v[142:145], v[110:125]
	s_waitcnt lgkmcnt(8)
	v_mfma_f32_32x32x16_bf16 v[110:125], v[228:231], v[146:149], v[110:125]
	s_waitcnt lgkmcnt(6)
	v_mfma_f32_32x32x16_bf16 v[110:125], v[232:235], v[150:153], v[110:125]
	s_waitcnt lgkmcnt(4)
	v_mfma_f32_32x32x16_bf16 v[110:125], v[236:239], v[154:157], v[110:125]
	s_waitcnt lgkmcnt(2)
	v_mfma_f32_32x32x16_bf16 v[110:125], v[240:243], v[158:161], v[110:125]
	s_waitcnt lgkmcnt(0)
	v_mfma_f32_32x32x16_bf16 v[110:125], v[244:247], v[162:165], v[110:125]
	s_nop 7
	s_nop 3
	s_mov_b64 exec, s[44:45]
	ds_write_b32 v202, v110 offset:0
	ds_write_b32 v202, v111 offset:64
	ds_write_b32 v202, v112 offset:128
	ds_write_b32 v202, v113 offset:192
	ds_write_b32 v202, v114 offset:512
	ds_write_b32 v202, v115 offset:576
	ds_write_b32 v202, v116 offset:640
	ds_write_b32 v202, v117 offset:704
	ds_write_b32 v202, v118 offset:1024
	ds_write_b32 v202, v119 offset:1088
	ds_write_b32 v202, v120 offset:1152
	ds_write_b32 v202, v121 offset:1216
	ds_write_b32 v202, v122 offset:1536
	ds_write_b32 v202, v123 offset:1600
	ds_write_b32 v202, v124 offset:1664
	ds_write_b32 v202, v125 offset:1728
	s_mov_b64 exec, -1
	s_waitcnt lgkmcnt(0)
	ds_read_b128 v[216:219], v203
	ds_read_b128 v[220:223], v203 offset:16
	s_waitcnt lgkmcnt(0)
	v_mul_f32_e32 v224, 0x3d372713, v216
	v_mul_f32_e32 v225, 0x3d372713, v217
	v_mul_f32_e32 v226, 0x3d372713, v218
	v_mul_f32_e32 v227, 0x3d372713, v219
	v_mul_f32_e32 v228, 0x3d372713, v220
	v_mul_f32_e32 v229, 0x3d372713, v221
	v_mul_f32_e32 v230, 0x3d372713, v222
	v_mul_f32_e32 v231, 0x3d372713, v223
	v_mul_f32_e32 v224, v216, v224
	v_mul_f32_e32 v225, v217, v225
	v_mul_f32_e32 v226, v218, v226
	v_mul_f32_e32 v227, v219, v227
	v_mul_f32_e32 v228, v220, v228
	v_mul_f32_e32 v229, v221, v229
	v_mul_f32_e32 v230, v222, v230
	v_mul_f32_e32 v231, v223, v231
	v_fma_f32 v224, v216, v224, v216
	v_fma_f32 v225, v217, v225, v217
	v_fma_f32 v226, v218, v226, v218
	v_fma_f32 v227, v219, v227, v219
	v_fma_f32 v228, v220, v228, v220
	v_fma_f32 v229, v221, v229, v221
	v_fma_f32 v230, v222, v230, v222
	v_fma_f32 v231, v223, v231, v223
	v_mul_f32_e32 v224, 0x3f4c422a, v224
	v_mul_f32_e32 v225, 0x3f4c422a, v225
	v_mul_f32_e32 v226, 0x3f4c422a, v226
	v_mul_f32_e32 v227, 0x3f4c422a, v227
	v_mul_f32_e32 v228, 0x3f4c422a, v228
	v_mul_f32_e32 v229, 0x3f4c422a, v229
	v_mul_f32_e32 v230, 0x3f4c422a, v230
	v_mul_f32_e32 v231, 0x3f4c422a, v231
	v_add_f32_e32 v224, v224, v224
	v_add_f32_e32 v225, v225, v225
	v_add_f32_e32 v226, v226, v226
	v_add_f32_e32 v227, v227, v227
	v_add_f32_e32 v228, v228, v228
	v_add_f32_e32 v229, v229, v229
	v_add_f32_e32 v230, v230, v230
	v_add_f32_e32 v231, v231, v231
	v_mul_f32_e32 v224, 0xbfb8aa3b, v224
	v_mul_f32_e32 v225, 0xbfb8aa3b, v225
	v_mul_f32_e32 v226, 0xbfb8aa3b, v226
	v_mul_f32_e32 v227, 0xbfb8aa3b, v227
	v_mul_f32_e32 v228, 0xbfb8aa3b, v228
	v_mul_f32_e32 v229, 0xbfb8aa3b, v229
	v_mul_f32_e32 v230, 0xbfb8aa3b, v230
	v_mul_f32_e32 v231, 0xbfb8aa3b, v231
	v_exp_f32_e32 v224, v224
	v_exp_f32_e32 v225, v225
	v_exp_f32_e32 v226, v226
	v_exp_f32_e32 v227, v227
	v_exp_f32_e32 v228, v228
	v_exp_f32_e32 v229, v229
	v_exp_f32_e32 v230, v230
	v_exp_f32_e32 v231, v231
	s_nop 0
	v_add_f32_e32 v224, 1.0, v224
	v_add_f32_e32 v225, 1.0, v225
	v_add_f32_e32 v226, 1.0, v226
	v_add_f32_e32 v227, 1.0, v227
	v_add_f32_e32 v228, 1.0, v228
	v_add_f32_e32 v229, 1.0, v229
	v_add_f32_e32 v230, 1.0, v230
	v_add_f32_e32 v231, 1.0, v231
	v_rcp_f32_e32 v224, v224
	v_rcp_f32_e32 v225, v225
	v_rcp_f32_e32 v226, v226
	v_rcp_f32_e32 v227, v227
	v_rcp_f32_e32 v228, v228
	v_rcp_f32_e32 v229, v229
	v_rcp_f32_e32 v230, v230
	v_rcp_f32_e32 v231, v231
	s_nop 0
	v_mul_f32_e32 v224, v216, v224
	v_mul_f32_e32 v225, v217, v225
	v_mul_f32_e32 v226, v218, v226
	v_mul_f32_e32 v227, v219, v227
	v_mul_f32_e32 v228, v220, v228
	v_mul_f32_e32 v229, v221, v229
	v_mul_f32_e32 v230, v222, v230
	v_mul_f32_e32 v231, v223, v231
	v_cvt_pk_bf16_f32 v232, v224, v225
	v_cvt_pk_bf16_f32 v233, v226, v227
	v_cvt_pk_bf16_f32 v234, v228, v229
	v_cvt_pk_bf16_f32 v235, v230, v231
	s_add_u32 s70, s60, 0x20000
	s_addc_u32 s71, s61, 0
	global_store_dwordx4 v205, v[232:235], s[70:71]
	s_waitcnt vmcnt(1)
	v_mfma_f32_32x32x16_bf16 v[46:61], v[126:129], v[26:29], 0
	v_mfma_f32_32x32x16_bf16 v[78:93], v[126:129], v[34:37], 0
	v_mfma_f32_32x32x16_bf16 v[62:77], v[126:129], v[30:33], 0
	v_mfma_f32_32x32x16_bf16 v[94:109], v[126:129], v[38:41], 0
	v_mfma_f32_32x32x16_bf16 v[110:125], v[126:129], v[42:45], 0
	s_add_u32 s70, s58, 0x60000
	s_addc_u32 s71, s59, 0
	global_load_dwordx4 v[130:133], v204, s[70:71]
	s_nop 7
	s_nop 1
	v_fmac_f32_e32 v47, v6, v46
	v_fmac_f32_e32 v79, v6, v78
	v_fma_f32 v47, -v7, v78, v47
	v_fmac_f32_e32 v79, v7, v46
	v_fmac_f32_e32 v51, v6, v50
	v_fmac_f32_e32 v83, v6, v82
	v_fma_f32 v51, -v7, v82, v51
	v_fmac_f32_e32 v83, v7, v50
	v_fmac_f32_e32 v55, v6, v54
	v_fmac_f32_e32 v87, v6, v86
	v_fma_f32 v55, -v7, v86, v55
	v_fmac_f32_e32 v87, v7, v54
	v_fmac_f32_e32 v59, v6, v58
	v_fmac_f32_e32 v91, v6, v90
	v_fma_f32 v59, -v7, v90, v59
	v_fmac_f32_e32 v91, v7, v58
	v_fmac_f32_e32 v63, v14, v62
	v_fmac_f32_e32 v95, v14, v94
	v_fma_f32 v63, -v15, v94, v63
	v_fmac_f32_e32 v95, v15, v62
	v_fmac_f32_e32 v67, v14, v66
	v_fmac_f32_e32 v99, v14, v98
	v_fma_f32 v67, -v15, v98, v67
	v_fmac_f32_e32 v99, v15, v66
	v_fmac_f32_e32 v71, v14, v70
	v_fmac_f32_e32 v103, v14, v102
	v_fma_f32 v71, -v15, v102, v71
	v_fmac_f32_e32 v103, v15, v70
	v_fmac_f32_e32 v75, v14, v74
	v_fmac_f32_e32 v107, v14, v106
	v_fma_f32 v75, -v15, v106, v75
	v_fmac_f32_e32 v107, v15, v74
	v_fmac_f32_e32 v48, v6, v47
	v_fmac_f32_e32 v80, v6, v79
	v_fma_f32 v48, -v7, v79, v48
	v_fmac_f32_e32 v80, v7, v47
	v_fmac_f32_e32 v52, v6, v51
	v_fmac_f32_e32 v84, v6, v83
	v_fma_f32 v52, -v7, v83, v52
	v_fmac_f32_e32 v84, v7, v51
	v_fmac_f32_e32 v56, v6, v55
	v_fmac_f32_e32 v88, v6, v87
	v_fma_f32 v56, -v7, v87, v56
	v_fmac_f32_e32 v88, v7, v55
	v_fmac_f32_e32 v60, v6, v59
	v_fmac_f32_e32 v92, v6, v91
	v_fma_f32 v60, -v7, v91, v60
	v_fmac_f32_e32 v92, v7, v59
	v_fmac_f32_e32 v64, v14, v63
	v_fmac_f32_e32 v96, v14, v95
	v_fma_f32 v64, -v15, v95, v64
	v_fmac_f32_e32 v96, v15, v63
	v_fmac_f32_e32 v68, v14, v67
	v_fmac_f32_e32 v100, v14, v99
	v_fma_f32 v68, -v15, v99, v68
	v_fmac_f32_e32 v100, v15, v67
	v_fmac_f32_e32 v72, v14, v71
	v_fmac_f32_e32 v104, v14, v103
	v_fma_f32 v72, -v15, v103, v72
	v_fmac_f32_e32 v104, v15, v71
	v_fmac_f32_e32 v76, v14, v75
	v_fmac_f32_e32 v108, v14, v107
	v_fma_f32 v76, -v15, v107, v76
	v_fmac_f32_e32 v108, v15, v75
	v_fmac_f32_e32 v49, v6, v48
	v_fmac_f32_e32 v81, v6, v80
	v_fma_f32 v49, -v7, v80, v49
	v_fmac_f32_e32 v81, v7, v48
	v_fmac_f32_e32 v53, v6, v52
	v_fmac_f32_e32 v85, v6, v84
	v_fma_f32 v53, -v7, v84, v53
	v_fmac_f32_e32 v85, v7, v52
	v_fmac_f32_e32 v57, v6, v56
	v_fmac_f32_e32 v89, v6, v88
	v_fma_f32 v57, -v7, v88, v57
	v_fmac_f32_e32 v89, v7, v56
	v_fmac_f32_e32 v61, v6, v60
	v_fmac_f32_e32 v93, v6, v92
	v_fma_f32 v61, -v7, v92, v61
	v_fmac_f32_e32 v93, v7, v60
	v_fmac_f32_e32 v65, v14, v64
	v_fmac_f32_e32 v97, v14, v96
	v_fma_f32 v65, -v15, v96, v65
	v_fmac_f32_e32 v97, v15, v64
	v_fmac_f32_e32 v69, v14, v68
	v_fmac_f32_e32 v101, v14, v100
	v_fma_f32 v69, -v15, v100, v69
	v_fmac_f32_e32 v101, v15, v68
	v_fmac_f32_e32 v73, v14, v72
	v_fmac_f32_e32 v105, v14, v104
	v_fma_f32 v73, -v15, v104, v73
	v_fmac_f32_e32 v105, v15, v72
	v_fmac_f32_e32 v77, v14, v76
	v_fmac_f32_e32 v109, v14, v108
	v_fma_f32 v77, -v15, v108, v77
	v_fmac_f32_e32 v109, v15, v76
	ds_bpermute_b32 v167, v199, v49
	ds_bpermute_b32 v168, v199, v81
	ds_bpermute_b32 v169, v199, v53
	ds_bpermute_b32 v170, v199, v85
	ds_bpermute_b32 v171, v199, v57
	ds_bpermute_b32 v172, v199, v89
	ds_bpermute_b32 v173, v199, v61
	ds_bpermute_b32 v174, v199, v93
	ds_bpermute_b32 v175, v199, v65
	ds_bpermute_b32 v176, v199, v97
	ds_bpermute_b32 v177, v199, v69
	ds_bpermute_b32 v178, v199, v101
	ds_bpermute_b32 v179, v199, v73
	ds_bpermute_b32 v180, v199, v105
	ds_bpermute_b32 v181, v199, v77
	ds_bpermute_b32 v182, v199, v109
	s_waitcnt lgkmcnt(0)
	v_cndmask_b32_e64 v216, v49, v167, s[40:41]
	v_cndmask_b32_e64 v217, v81, v168, s[40:41]
	v_cndmask_b32_e64 v218, v167, v49, s[40:41]
	v_cndmask_b32_e64 v219, v168, v81, s[40:41]
	v_fma_f32 v213, v12, v22, v216
	v_fma_f32 v214, v12, v23, v217
	v_fma_f32 v213, -v13, v23, v213
	v_fmac_f32_e32 v214, v13, v22
	v_fma_f32 v215, v12, v213, v218
	v_fma_f32 v248, v12, v214, v219
	v_fma_f32 v215, -v13, v214, v215
	v_fmac_f32_e32 v248, v13, v213
	v_cndmask_b32_e64 v183, v22, v213, s[40:41]
	v_cndmask_b32_e64 v184, v23, v214, s[40:41]
	v_cndmask_b32_e64 v224, v65, v175, s[40:41]
	v_cndmask_b32_e64 v225, v97, v176, s[40:41]
	v_cndmask_b32_e64 v226, v175, v65, s[40:41]
	v_cndmask_b32_e64 v227, v176, v97, s[40:41]
	v_fma_f32 v251, v20, v24, v224
	v_fma_f32 v252, v20, v25, v225
	v_fma_f32 v251, -v21, v25, v251
	v_fmac_f32_e32 v252, v21, v24
	v_fma_f32 v253, v20, v251, v226
	v_fma_f32 v211, v20, v252, v227
	v_fma_f32 v253, -v21, v252, v253
	v_fmac_f32_e32 v211, v21, v251
	v_cndmask_b32_e64 v191, v24, v251, s[40:41]
	v_cndmask_b32_e64 v192, v25, v252, s[40:41]
	v_cndmask_b32_e64 v216, v53, v169, s[40:41]
	v_cndmask_b32_e64 v217, v85, v170, s[40:41]
	v_cndmask_b32_e64 v218, v169, v53, s[40:41]
	v_cndmask_b32_e64 v219, v170, v85, s[40:41]
	v_fma_f32 v249, v12, v215, v216
	v_fma_f32 v250, v12, v248, v217
	v_fma_f32 v249, -v13, v248, v249
	v_fmac_f32_e32 v250, v13, v215
	v_fma_f32 v213, v12, v249, v218
	v_fma_f32 v214, v12, v250, v219
	v_fma_f32 v213, -v13, v250, v213
	v_fmac_f32_e32 v214, v13, v249
	v_cndmask_b32_e64 v185, v215, v249, s[40:41]
	v_cndmask_b32_e64 v186, v248, v250, s[40:41]
	v_cndmask_b32_e64 v224, v69, v177, s[40:41]
	v_cndmask_b32_e64 v225, v101, v178, s[40:41]
	v_cndmask_b32_e64 v226, v177, v69, s[40:41]
	v_cndmask_b32_e64 v227, v178, v101, s[40:41]
	v_fma_f32 v212, v20, v253, v224
	v_fma_f32 v209, v20, v211, v225
	v_fma_f32 v212, -v21, v211, v212
	v_fmac_f32_e32 v209, v21, v253
	v_fma_f32 v251, v20, v212, v226
	v_fma_f32 v252, v20, v209, v227
	v_fma_f32 v251, -v21, v209, v251
	v_fmac_f32_e32 v252, v21, v212
	v_cndmask_b32_e64 v193, v253, v212, s[40:41]
	v_cndmask_b32_e64 v194, v211, v209, s[40:41]
	v_cndmask_b32_e64 v216, v57, v171, s[40:41]
	v_cndmask_b32_e64 v217, v89, v172, s[40:41]
	v_cndmask_b32_e64 v218, v171, v57, s[40:41]
	v_cndmask_b32_e64 v219, v172, v89, s[40:41]
	v_fma_f32 v215, v12, v213, v216
	v_fma_f32 v248, v12, v214, v217
	v_fma_f32 v215, -v13, v214, v215
	v_fmac_f32_e32 v248, v13, v213
	v_fma_f32 v249, v12, v215, v218
	v_fma_f32 v250, v12, v248, v219
	v_fma_f32 v249, -v13, v248, v249
	v_fmac_f32_e32 v250, v13, v215
	v_cndmask_b32_e64 v187, v213, v215, s[40:41]
	v_cndmask_b32_e64 v188, v214, v248, s[40:41]
	v_cndmask_b32_e64 v224, v73, v179, s[40:41]
	v_cndmask_b32_e64 v225, v105, v180, s[40:41]
	v_cndmask_b32_e64 v226, v179, v73, s[40:41]
	v_cndmask_b32_e64 v227, v180, v105, s[40:41]
	v_fma_f32 v253, v20, v251, v224
	v_fma_f32 v211, v20, v252, v225
	v_fma_f32 v253, -v21, v252, v253
	v_fmac_f32_e32 v211, v21, v251
	v_fma_f32 v212, v20, v253, v226
	v_fma_f32 v209, v20, v211, v227
	v_fma_f32 v212, -v21, v211, v212
	v_fmac_f32_e32 v209, v21, v253
	v_cndmask_b32_e64 v195, v251, v253, s[40:41]
	v_cndmask_b32_e64 v196, v252, v211, s[40:41]
	v_cndmask_b32_e64 v216, v61, v173, s[40:41]
	v_cndmask_b32_e64 v217, v93, v174, s[40:41]
	v_cndmask_b32_e64 v218, v173, v61, s[40:41]
	v_cndmask_b32_e64 v219, v174, v93, s[40:41]
	v_fma_f32 v213, v12, v249, v216
	v_fma_f32 v214, v12, v250, v217
	v_fma_f32 v213, -v13, v250, v213
	v_fmac_f32_e32 v214, v13, v249
	v_fma_f32 v215, v12, v213, v218
	v_fma_f32 v248, v12, v214, v219
	v_fma_f32 v215, -v13, v214, v215
	v_fmac_f32_e32 v248, v13, v213
	v_cndmask_b32_e64 v189, v249, v213, s[40:41]
	v_cndmask_b32_e64 v190, v250, v214, s[40:41]
	v_cndmask_b32_e64 v224, v77, v181, s[40:41]
	v_cndmask_b32_e64 v225, v109, v182, s[40:41]
	v_cndmask_b32_e64 v226, v181, v77, s[40:41]
	v_cndmask_b32_e64 v227, v182, v109, s[40:41]
	v_fma_f32 v251, v20, v212, v224
	v_fma_f32 v252, v20, v209, v225
	v_fma_f32 v251, -v21, v209, v251
	v_fmac_f32_e32 v252, v21, v212
	v_fma_f32 v253, v20, v251, v226
	v_fma_f32 v211, v20, v252, v227
	v_fma_f32 v253, -v21, v252, v253
	v_fmac_f32_e32 v211, v21, v251
	v_cndmask_b32_e64 v197, v212, v251, s[40:41]
	v_cndmask_b32_e64 v198, v209, v252, s[40:41]
	v_mov_b32_e32 v22, v215
	v_mov_b32_e32 v23, v248
	v_mov_b32_e32 v24, v253
	v_mov_b32_e32 v25, v211
	v_fmac_f32_e32 v46, v6, v183
	v_fmac_f32_e32 v78, v6, v184
	v_fma_f32 v46, -v7, v184, v46
	v_fmac_f32_e32 v78, v7, v183
	v_fmac_f32_e32 v47, v8, v183
	v_fmac_f32_e32 v79, v8, v184
	v_fma_f32 v47, -v9, v184, v47
	v_fmac_f32_e32 v79, v9, v183
	v_fmac_f32_e32 v48, v10, v183
	v_fmac_f32_e32 v80, v10, v184
	v_fma_f32 v48, -v11, v184, v48
	v_fmac_f32_e32 v80, v11, v183
	v_fmac_f32_e32 v49, v12, v183
	v_fmac_f32_e32 v81, v12, v184
	v_fma_f32 v49, -v13, v184, v49
	v_fmac_f32_e32 v81, v13, v183
	v_fmac_f32_e32 v50, v6, v185
	v_fmac_f32_e32 v82, v6, v186
	v_fma_f32 v50, -v7, v186, v50
	v_fmac_f32_e32 v82, v7, v185
	v_fmac_f32_e32 v51, v8, v185
	v_fmac_f32_e32 v83, v8, v186
	v_fma_f32 v51, -v9, v186, v51
	v_fmac_f32_e32 v83, v9, v185
	v_fmac_f32_e32 v52, v10, v185
	v_fmac_f32_e32 v84, v10, v186
	v_fma_f32 v52, -v11, v186, v52
	v_fmac_f32_e32 v84, v11, v185
	v_fmac_f32_e32 v53, v12, v185
	v_fmac_f32_e32 v85, v12, v186
	v_fma_f32 v53, -v13, v186, v53
	v_fmac_f32_e32 v85, v13, v185
	v_fmac_f32_e32 v54, v6, v187
	v_fmac_f32_e32 v86, v6, v188
	v_fma_f32 v54, -v7, v188, v54
	v_fmac_f32_e32 v86, v7, v187
	v_fmac_f32_e32 v55, v8, v187
	v_fmac_f32_e32 v87, v8, v188
	v_fma_f32 v55, -v9, v188, v55
	v_fmac_f32_e32 v87, v9, v187
	v_fmac_f32_e32 v56, v10, v187
	v_fmac_f32_e32 v88, v10, v188
	v_fma_f32 v56, -v11, v188, v56
	v_fmac_f32_e32 v88, v11, v187
	v_fmac_f32_e32 v57, v12, v187
	v_fmac_f32_e32 v89, v12, v188
	v_fma_f32 v57, -v13, v188, v57
	v_fmac_f32_e32 v89, v13, v187
	v_fmac_f32_e32 v58, v6, v189
	v_fmac_f32_e32 v90, v6, v190
	v_fma_f32 v58, -v7, v190, v58
	v_fmac_f32_e32 v90, v7, v189
	v_fmac_f32_e32 v59, v8, v189
	v_fmac_f32_e32 v91, v8, v190
	v_fma_f32 v59, -v9, v190, v59
	v_fmac_f32_e32 v91, v9, v189
	v_fmac_f32_e32 v60, v10, v189
	v_fmac_f32_e32 v92, v10, v190
	v_fma_f32 v60, -v11, v190, v60
	v_fmac_f32_e32 v92, v11, v189
	v_fmac_f32_e32 v61, v12, v189
	v_fmac_f32_e32 v93, v12, v190
	v_fma_f32 v61, -v13, v190, v61
	v_fmac_f32_e32 v93, v13, v189
	v_fmac_f32_e32 v62, v14, v191
	v_fmac_f32_e32 v94, v14, v192
	v_fma_f32 v62, -v15, v192, v62
	v_fmac_f32_e32 v94, v15, v191
	v_fmac_f32_e32 v63, v16, v191
	v_fmac_f32_e32 v95, v16, v192
	v_fma_f32 v63, -v17, v192, v63
	v_fmac_f32_e32 v95, v17, v191
	v_fmac_f32_e32 v64, v18, v191
	v_fmac_f32_e32 v96, v18, v192
	v_fma_f32 v64, -v19, v192, v64
	v_fmac_f32_e32 v96, v19, v191
	v_fmac_f32_e32 v65, v20, v191
	v_fmac_f32_e32 v97, v20, v192
	v_fma_f32 v65, -v21, v192, v65
	v_fmac_f32_e32 v97, v21, v191
	v_fmac_f32_e32 v66, v14, v193
	v_fmac_f32_e32 v98, v14, v194
	v_fma_f32 v66, -v15, v194, v66
	v_fmac_f32_e32 v98, v15, v193
	v_fmac_f32_e32 v67, v16, v193
	v_fmac_f32_e32 v99, v16, v194
	v_fma_f32 v67, -v17, v194, v67
	v_fmac_f32_e32 v99, v17, v193
	v_fmac_f32_e32 v68, v18, v193
	v_fmac_f32_e32 v100, v18, v194
	v_fma_f32 v68, -v19, v194, v68
	v_fmac_f32_e32 v100, v19, v193
	v_fmac_f32_e32 v69, v20, v193
	v_fmac_f32_e32 v101, v20, v194
	v_fma_f32 v69, -v21, v194, v69
	v_fmac_f32_e32 v101, v21, v193
	v_fmac_f32_e32 v70, v14, v195
	v_fmac_f32_e32 v102, v14, v196
	v_fma_f32 v70, -v15, v196, v70
	v_fmac_f32_e32 v102, v15, v195
	v_fmac_f32_e32 v71, v16, v195
	v_fmac_f32_e32 v103, v16, v196
	v_fma_f32 v71, -v17, v196, v71
	v_fmac_f32_e32 v103, v17, v195
	v_fmac_f32_e32 v72, v18, v195
	v_fmac_f32_e32 v104, v18, v196
	v_fma_f32 v72, -v19, v196, v72
	v_fmac_f32_e32 v104, v19, v195
	v_fmac_f32_e32 v73, v20, v195
	v_fmac_f32_e32 v105, v20, v196
	v_fma_f32 v73, -v21, v196, v73
	v_fmac_f32_e32 v105, v21, v195
	v_fmac_f32_e32 v74, v14, v197
	v_fmac_f32_e32 v106, v14, v198
	v_fma_f32 v74, -v15, v198, v74
	v_fmac_f32_e32 v106, v15, v197
	v_fmac_f32_e32 v75, v16, v197
	v_fmac_f32_e32 v107, v16, v198
	v_fma_f32 v75, -v17, v198, v75
	v_fmac_f32_e32 v107, v17, v197
	v_fmac_f32_e32 v76, v18, v197
	v_fmac_f32_e32 v108, v18, v198
	v_fma_f32 v76, -v19, v198, v76
	v_fmac_f32_e32 v108, v19, v197
	v_fmac_f32_e32 v77, v20, v197
	v_fmac_f32_e32 v109, v20, v198
	v_fma_f32 v77, -v21, v198, v77
	v_fmac_f32_e32 v109, v21, v197
	v_cvt_pk_bf16_f32 v216, v46, v47
	v_cvt_pk_bf16_f32 v217, v48, v49
	ds_write_b64 v200, v[216:217] offset:0
	v_cvt_pk_bf16_f32 v218, v50, v51
	v_cvt_pk_bf16_f32 v219, v52, v53
	ds_write_b64 v200, v[218:219] offset:16
	v_cvt_pk_bf16_f32 v220, v54, v55
	v_cvt_pk_bf16_f32 v221, v56, v57
	ds_write_b64 v200, v[220:221] offset:32
	v_cvt_pk_bf16_f32 v222, v58, v59
	v_cvt_pk_bf16_f32 v223, v60, v61
	ds_write_b64 v200, v[222:223] offset:48
	v_cvt_pk_bf16_f32 v224, v62, v63
	v_cvt_pk_bf16_f32 v225, v64, v65
	ds_write_b64 v200, v[224:225] offset:2048
	v_cvt_pk_bf16_f32 v226, v66, v67
	v_cvt_pk_bf16_f32 v227, v68, v69
	ds_write_b64 v200, v[226:227] offset:2064
	v_cvt_pk_bf16_f32 v228, v70, v71
	v_cvt_pk_bf16_f32 v229, v72, v73
	ds_write_b64 v200, v[228:229] offset:2080
	v_cvt_pk_bf16_f32 v230, v74, v75
	v_cvt_pk_bf16_f32 v231, v76, v77
	ds_write_b64 v200, v[230:231] offset:2096
	v_cvt_pk_bf16_f32 v232, v78, v79
	v_cvt_pk_bf16_f32 v233, v80, v81
	ds_write_b64 v200, v[232:233] offset:4096
	v_cvt_pk_bf16_f32 v234, v82, v83
	v_cvt_pk_bf16_f32 v235, v84, v85
	ds_write_b64 v200, v[234:235] offset:4112
	v_cvt_pk_bf16_f32 v236, v86, v87
	v_cvt_pk_bf16_f32 v237, v88, v89
	ds_write_b64 v200, v[236:237] offset:4128
	v_cvt_pk_bf16_f32 v238, v90, v91
	v_cvt_pk_bf16_f32 v239, v92, v93
	ds_write_b64 v200, v[238:239] offset:4144
	v_cvt_pk_bf16_f32 v240, v94, v95
	v_cvt_pk_bf16_f32 v241, v96, v97
	ds_write_b64 v200, v[240:241] offset:6144
	v_cvt_pk_bf16_f32 v242, v98, v99
	v_cvt_pk_bf16_f32 v243, v100, v101
	ds_write_b64 v200, v[242:243] offset:6160
	v_cvt_pk_bf16_f32 v244, v102, v103
	v_cvt_pk_bf16_f32 v245, v104, v105
	ds_write_b64 v200, v[244:245] offset:6176
	v_cvt_pk_bf16_f32 v246, v106, v107
	v_cvt_pk_bf16_f32 v247, v108, v109
	ds_write_b64 v200, v[246:247] offset:6192
	s_waitcnt lgkmcnt(0)
	ds_read_b64_tr_b16 v[216:217], v201 offset:0
	ds_read_b64_tr_b16 v[218:219], v201 offset:256
	ds_read_b64_tr_b16 v[220:221], v201 offset:1024
	ds_read_b64_tr_b16 v[222:223], v201 offset:1280
	ds_read_b64_tr_b16 v[224:225], v201 offset:2048
	ds_read_b64_tr_b16 v[226:227], v201 offset:2304
	ds_read_b64_tr_b16 v[228:229], v201 offset:3072
	ds_read_b64_tr_b16 v[230:231], v201 offset:3328
	ds_read_b64_tr_b16 v[232:233], v201 offset:4096
	ds_read_b64_tr_b16 v[234:235], v201 offset:4352
	ds_read_b64_tr_b16 v[236:237], v201 offset:5120
	ds_read_b64_tr_b16 v[238:239], v201 offset:5376
	ds_read_b64_tr_b16 v[240:241], v201 offset:6144
	ds_read_b64_tr_b16 v[242:243], v201 offset:6400
	ds_read_b64_tr_b16 v[244:245], v201 offset:7168
	ds_read_b64_tr_b16 v[246:247], v201 offset:7424
	s_waitcnt lgkmcnt(14)
	v_mfma_f32_32x32x16_bf16 v[110:125], v[216:219], v[134:137], v[110:125]
	s_waitcnt lgkmcnt(12)
	v_mfma_f32_32x32x16_bf16 v[110:125], v[220:223], v[138:141], v[110:125]
	s_waitcnt lgkmcnt(10)
	v_mfma_f32_32x32x16_bf16 v[110:125], v[224:227], v[142:145], v[110:125]
	s_waitcnt lgkmcnt(8)
	v_mfma_f32_32x32x16_bf16 v[110:125], v[228:231], v[146:149], v[110:125]
	s_waitcnt lgkmcnt(6)
	v_mfma_f32_32x32x16_bf16 v[110:125], v[232:235], v[150:153], v[110:125]
	s_waitcnt lgkmcnt(4)
	v_mfma_f32_32x32x16_bf16 v[110:125], v[236:239], v[154:157], v[110:125]
	s_waitcnt lgkmcnt(2)
	v_mfma_f32_32x32x16_bf16 v[110:125], v[240:243], v[158:161], v[110:125]
	s_waitcnt lgkmcnt(0)
	v_mfma_f32_32x32x16_bf16 v[110:125], v[244:247], v[162:165], v[110:125]
	s_nop 7
	s_nop 3
	s_mov_b64 exec, s[44:45]
	ds_write_b32 v202, v110 offset:0
	ds_write_b32 v202, v111 offset:64
	ds_write_b32 v202, v112 offset:128
	ds_write_b32 v202, v113 offset:192
	ds_write_b32 v202, v114 offset:512
	ds_write_b32 v202, v115 offset:576
	ds_write_b32 v202, v116 offset:640
	ds_write_b32 v202, v117 offset:704
	ds_write_b32 v202, v118 offset:1024
	ds_write_b32 v202, v119 offset:1088
	ds_write_b32 v202, v120 offset:1152
	ds_write_b32 v202, v121 offset:1216
	ds_write_b32 v202, v122 offset:1536
	ds_write_b32 v202, v123 offset:1600
	ds_write_b32 v202, v124 offset:1664
	ds_write_b32 v202, v125 offset:1728
	s_mov_b64 exec, -1
	s_waitcnt lgkmcnt(0)
	ds_read_b128 v[216:219], v203
	ds_read_b128 v[220:223], v203 offset:16
	s_waitcnt lgkmcnt(0)
	v_mul_f32_e32 v224, 0x3d372713, v216
	v_mul_f32_e32 v225, 0x3d372713, v217
	v_mul_f32_e32 v226, 0x3d372713, v218
	v_mul_f32_e32 v227, 0x3d372713, v219
	v_mul_f32_e32 v228, 0x3d372713, v220
	v_mul_f32_e32 v229, 0x3d372713, v221
	v_mul_f32_e32 v230, 0x3d372713, v222
	v_mul_f32_e32 v231, 0x3d372713, v223
	v_mul_f32_e32 v224, v216, v224
	v_mul_f32_e32 v225, v217, v225
	v_mul_f32_e32 v226, v218, v226
	v_mul_f32_e32 v227, v219, v227
	v_mul_f32_e32 v228, v220, v228
	v_mul_f32_e32 v229, v221, v229
	v_mul_f32_e32 v230, v222, v230
	v_mul_f32_e32 v231, v223, v231
	v_fma_f32 v224, v216, v224, v216
	v_fma_f32 v225, v217, v225, v217
	v_fma_f32 v226, v218, v226, v218
	v_fma_f32 v227, v219, v227, v219
	v_fma_f32 v228, v220, v228, v220
	v_fma_f32 v229, v221, v229, v221
	v_fma_f32 v230, v222, v230, v222
	v_fma_f32 v231, v223, v231, v223
	v_mul_f32_e32 v224, 0x3f4c422a, v224
	v_mul_f32_e32 v225, 0x3f4c422a, v225
	v_mul_f32_e32 v226, 0x3f4c422a, v226
	v_mul_f32_e32 v227, 0x3f4c422a, v227
	v_mul_f32_e32 v228, 0x3f4c422a, v228
	v_mul_f32_e32 v229, 0x3f4c422a, v229
	v_mul_f32_e32 v230, 0x3f4c422a, v230
	v_mul_f32_e32 v231, 0x3f4c422a, v231
	v_add_f32_e32 v224, v224, v224
	v_add_f32_e32 v225, v225, v225
	v_add_f32_e32 v226, v226, v226
	v_add_f32_e32 v227, v227, v227
	v_add_f32_e32 v228, v228, v228
	v_add_f32_e32 v229, v229, v229
	v_add_f32_e32 v230, v230, v230
	v_add_f32_e32 v231, v231, v231
	v_mul_f32_e32 v224, 0xbfb8aa3b, v224
	v_mul_f32_e32 v225, 0xbfb8aa3b, v225
	v_mul_f32_e32 v226, 0xbfb8aa3b, v226
	v_mul_f32_e32 v227, 0xbfb8aa3b, v227
	v_mul_f32_e32 v228, 0xbfb8aa3b, v228
	v_mul_f32_e32 v229, 0xbfb8aa3b, v229
	v_mul_f32_e32 v230, 0xbfb8aa3b, v230
	v_mul_f32_e32 v231, 0xbfb8aa3b, v231
	v_exp_f32_e32 v224, v224
	v_exp_f32_e32 v225, v225
	v_exp_f32_e32 v226, v226
	v_exp_f32_e32 v227, v227
	v_exp_f32_e32 v228, v228
	v_exp_f32_e32 v229, v229
	v_exp_f32_e32 v230, v230
	v_exp_f32_e32 v231, v231
	s_nop 0
	v_add_f32_e32 v224, 1.0, v224
	v_add_f32_e32 v225, 1.0, v225
	v_add_f32_e32 v226, 1.0, v226
	v_add_f32_e32 v227, 1.0, v227
	v_add_f32_e32 v228, 1.0, v228
	v_add_f32_e32 v229, 1.0, v229
	v_add_f32_e32 v230, 1.0, v230
	v_add_f32_e32 v231, 1.0, v231
	v_rcp_f32_e32 v224, v224
	v_rcp_f32_e32 v225, v225
	v_rcp_f32_e32 v226, v226
	v_rcp_f32_e32 v227, v227
	v_rcp_f32_e32 v228, v228
	v_rcp_f32_e32 v229, v229
	v_rcp_f32_e32 v230, v230
	v_rcp_f32_e32 v231, v231
	s_nop 0
	v_mul_f32_e32 v224, v216, v224
	v_mul_f32_e32 v225, v217, v225
	v_mul_f32_e32 v226, v218, v226
	v_mul_f32_e32 v227, v219, v227
	v_mul_f32_e32 v228, v220, v228
	v_mul_f32_e32 v229, v221, v229
	v_mul_f32_e32 v230, v222, v230
	v_mul_f32_e32 v231, v223, v231
	v_cvt_pk_bf16_f32 v232, v224, v225
	v_cvt_pk_bf16_f32 v233, v226, v227
	v_cvt_pk_bf16_f32 v234, v228, v229
	v_cvt_pk_bf16_f32 v235, v230, v231
	s_add_u32 s70, s60, 0x40000
	s_addc_u32 s71, s61, 0
	global_store_dwordx4 v205, v[232:235], s[70:71]
	s_waitcnt vmcnt(1)
	v_mfma_f32_32x32x16_bf16 v[46:61], v[130:133], v[26:29], 0
	v_mfma_f32_32x32x16_bf16 v[78:93], v[130:133], v[34:37], 0
	v_mfma_f32_32x32x16_bf16 v[62:77], v[130:133], v[30:33], 0
	v_mfma_f32_32x32x16_bf16 v[94:109], v[130:133], v[38:41], 0
	v_mfma_f32_32x32x16_bf16 v[110:125], v[130:133], v[42:45], 0
	s_nop 7
	s_nop 1
	v_fmac_f32_e32 v47, v6, v46
	v_fmac_f32_e32 v79, v6, v78
	v_fma_f32 v47, -v7, v78, v47
	v_fmac_f32_e32 v79, v7, v46
	v_fmac_f32_e32 v51, v6, v50
	v_fmac_f32_e32 v83, v6, v82
	v_fma_f32 v51, -v7, v82, v51
	v_fmac_f32_e32 v83, v7, v50
	v_fmac_f32_e32 v55, v6, v54
	v_fmac_f32_e32 v87, v6, v86
	v_fma_f32 v55, -v7, v86, v55
	v_fmac_f32_e32 v87, v7, v54
	v_fmac_f32_e32 v59, v6, v58
	v_fmac_f32_e32 v91, v6, v90
	v_fma_f32 v59, -v7, v90, v59
	v_fmac_f32_e32 v91, v7, v58
	v_fmac_f32_e32 v63, v14, v62
	v_fmac_f32_e32 v95, v14, v94
	v_fma_f32 v63, -v15, v94, v63
	v_fmac_f32_e32 v95, v15, v62
	v_fmac_f32_e32 v67, v14, v66
	v_fmac_f32_e32 v99, v14, v98
	v_fma_f32 v67, -v15, v98, v67
	v_fmac_f32_e32 v99, v15, v66
	v_fmac_f32_e32 v71, v14, v70
	v_fmac_f32_e32 v103, v14, v102
	v_fma_f32 v71, -v15, v102, v71
	v_fmac_f32_e32 v103, v15, v70
	v_fmac_f32_e32 v75, v14, v74
	v_fmac_f32_e32 v107, v14, v106
	v_fma_f32 v75, -v15, v106, v75
	v_fmac_f32_e32 v107, v15, v74
	v_fmac_f32_e32 v48, v6, v47
	v_fmac_f32_e32 v80, v6, v79
	v_fma_f32 v48, -v7, v79, v48
	v_fmac_f32_e32 v80, v7, v47
	v_fmac_f32_e32 v52, v6, v51
	v_fmac_f32_e32 v84, v6, v83
	v_fma_f32 v52, -v7, v83, v52
	v_fmac_f32_e32 v84, v7, v51
	v_fmac_f32_e32 v56, v6, v55
	v_fmac_f32_e32 v88, v6, v87
	v_fma_f32 v56, -v7, v87, v56
	v_fmac_f32_e32 v88, v7, v55
	v_fmac_f32_e32 v60, v6, v59
	v_fmac_f32_e32 v92, v6, v91
	v_fma_f32 v60, -v7, v91, v60
	v_fmac_f32_e32 v92, v7, v59
	v_fmac_f32_e32 v64, v14, v63
	v_fmac_f32_e32 v96, v14, v95
	v_fma_f32 v64, -v15, v95, v64
	v_fmac_f32_e32 v96, v15, v63
	v_fmac_f32_e32 v68, v14, v67
	v_fmac_f32_e32 v100, v14, v99
	v_fma_f32 v68, -v15, v99, v68
	v_fmac_f32_e32 v100, v15, v67
	v_fmac_f32_e32 v72, v14, v71
	v_fmac_f32_e32 v104, v14, v103
	v_fma_f32 v72, -v15, v103, v72
	v_fmac_f32_e32 v104, v15, v71
	v_fmac_f32_e32 v76, v14, v75
	v_fmac_f32_e32 v108, v14, v107
	v_fma_f32 v76, -v15, v107, v76
	v_fmac_f32_e32 v108, v15, v75
	v_fmac_f32_e32 v49, v6, v48
	v_fmac_f32_e32 v81, v6, v80
	v_fma_f32 v49, -v7, v80, v49
	v_fmac_f32_e32 v81, v7, v48
	v_fmac_f32_e32 v53, v6, v52
	v_fmac_f32_e32 v85, v6, v84
	v_fma_f32 v53, -v7, v84, v53
	v_fmac_f32_e32 v85, v7, v52
	v_fmac_f32_e32 v57, v6, v56
	v_fmac_f32_e32 v89, v6, v88
	v_fma_f32 v57, -v7, v88, v57
	v_fmac_f32_e32 v89, v7, v56
	v_fmac_f32_e32 v61, v6, v60
	v_fmac_f32_e32 v93, v6, v92
	v_fma_f32 v61, -v7, v92, v61
	v_fmac_f32_e32 v93, v7, v60
	v_fmac_f32_e32 v65, v14, v64
	v_fmac_f32_e32 v97, v14, v96
	v_fma_f32 v65, -v15, v96, v65
	v_fmac_f32_e32 v97, v15, v64
	v_fmac_f32_e32 v69, v14, v68
	v_fmac_f32_e32 v101, v14, v100
	v_fma_f32 v69, -v15, v100, v69
	v_fmac_f32_e32 v101, v15, v68
	v_fmac_f32_e32 v73, v14, v72
	v_fmac_f32_e32 v105, v14, v104
	v_fma_f32 v73, -v15, v104, v73
	v_fmac_f32_e32 v105, v15, v72
	v_fmac_f32_e32 v77, v14, v76
	v_fmac_f32_e32 v109, v14, v108
	v_fma_f32 v77, -v15, v108, v77
	v_fmac_f32_e32 v109, v15, v76
	ds_bpermute_b32 v167, v199, v49
	ds_bpermute_b32 v168, v199, v81
	ds_bpermute_b32 v169, v199, v53
	ds_bpermute_b32 v170, v199, v85
	ds_bpermute_b32 v171, v199, v57
	ds_bpermute_b32 v172, v199, v89
	ds_bpermute_b32 v173, v199, v61
	ds_bpermute_b32 v174, v199, v93
	ds_bpermute_b32 v175, v199, v65
	ds_bpermute_b32 v176, v199, v97
	ds_bpermute_b32 v177, v199, v69
	ds_bpermute_b32 v178, v199, v101
	ds_bpermute_b32 v179, v199, v73
	ds_bpermute_b32 v180, v199, v105
	ds_bpermute_b32 v181, v199, v77
	ds_bpermute_b32 v182, v199, v109
	s_waitcnt lgkmcnt(0)
	v_cndmask_b32_e64 v216, v49, v167, s[40:41]
	v_cndmask_b32_e64 v217, v81, v168, s[40:41]
	v_cndmask_b32_e64 v218, v167, v49, s[40:41]
	v_cndmask_b32_e64 v219, v168, v81, s[40:41]
	v_fma_f32 v213, v12, v22, v216
	v_fma_f32 v214, v12, v23, v217
	v_fma_f32 v213, -v13, v23, v213
	v_fmac_f32_e32 v214, v13, v22
	v_fma_f32 v215, v12, v213, v218
	v_fma_f32 v248, v12, v214, v219
	v_fma_f32 v215, -v13, v214, v215
	v_fmac_f32_e32 v248, v13, v213
	v_cndmask_b32_e64 v183, v22, v213, s[40:41]
	v_cndmask_b32_e64 v184, v23, v214, s[40:41]
	v_cndmask_b32_e64 v224, v65, v175, s[40:41]
	v_cndmask_b32_e64 v225, v97, v176, s[40:41]
	v_cndmask_b32_e64 v226, v175, v65, s[40:41]
	v_cndmask_b32_e64 v227, v176, v97, s[40:41]
	v_fma_f32 v251, v20, v24, v224
	v_fma_f32 v252, v20, v25, v225
	v_fma_f32 v251, -v21, v25, v251
	v_fmac_f32_e32 v252, v21, v24
	v_fma_f32 v253, v20, v251, v226
	v_fma_f32 v211, v20, v252, v227
	v_fma_f32 v253, -v21, v252, v253
	v_fmac_f32_e32 v211, v21, v251
	v_cndmask_b32_e64 v191, v24, v251, s[40:41]
	v_cndmask_b32_e64 v192, v25, v252, s[40:41]
	v_cndmask_b32_e64 v216, v53, v169, s[40:41]
	v_cndmask_b32_e64 v217, v85, v170, s[40:41]
	v_cndmask_b32_e64 v218, v169, v53, s[40:41]
	v_cndmask_b32_e64 v219, v170, v85, s[40:41]
	v_fma_f32 v249, v12, v215, v216
	v_fma_f32 v250, v12, v248, v217
	v_fma_f32 v249, -v13, v248, v249
	v_fmac_f32_e32 v250, v13, v215
	v_fma_f32 v213, v12, v249, v218
	v_fma_f32 v214, v12, v250, v219
	v_fma_f32 v213, -v13, v250, v213
	v_fmac_f32_e32 v214, v13, v249
	v_cndmask_b32_e64 v185, v215, v249, s[40:41]
	v_cndmask_b32_e64 v186, v248, v250, s[40:41]
	v_cndmask_b32_e64 v224, v69, v177, s[40:41]
	v_cndmask_b32_e64 v225, v101, v178, s[40:41]
	v_cndmask_b32_e64 v226, v177, v69, s[40:41]
	v_cndmask_b32_e64 v227, v178, v101, s[40:41]
	v_fma_f32 v212, v20, v253, v224
	v_fma_f32 v209, v20, v211, v225
	v_fma_f32 v212, -v21, v211, v212
	v_fmac_f32_e32 v209, v21, v253
	v_fma_f32 v251, v20, v212, v226
	v_fma_f32 v252, v20, v209, v227
	v_fma_f32 v251, -v21, v209, v251
	v_fmac_f32_e32 v252, v21, v212
	v_cndmask_b32_e64 v193, v253, v212, s[40:41]
	v_cndmask_b32_e64 v194, v211, v209, s[40:41]
	v_cndmask_b32_e64 v216, v57, v171, s[40:41]
	v_cndmask_b32_e64 v217, v89, v172, s[40:41]
	v_cndmask_b32_e64 v218, v171, v57, s[40:41]
	v_cndmask_b32_e64 v219, v172, v89, s[40:41]
	v_fma_f32 v215, v12, v213, v216
	v_fma_f32 v248, v12, v214, v217
	v_fma_f32 v215, -v13, v214, v215
	v_fmac_f32_e32 v248, v13, v213
	v_fma_f32 v249, v12, v215, v218
	v_fma_f32 v250, v12, v248, v219
	v_fma_f32 v249, -v13, v248, v249
	v_fmac_f32_e32 v250, v13, v215
	v_cndmask_b32_e64 v187, v213, v215, s[40:41]
	v_cndmask_b32_e64 v188, v214, v248, s[40:41]
	v_cndmask_b32_e64 v224, v73, v179, s[40:41]
	v_cndmask_b32_e64 v225, v105, v180, s[40:41]
	v_cndmask_b32_e64 v226, v179, v73, s[40:41]
	v_cndmask_b32_e64 v227, v180, v105, s[40:41]
	v_fma_f32 v253, v20, v251, v224
	v_fma_f32 v211, v20, v252, v225
	v_fma_f32 v253, -v21, v252, v253
	v_fmac_f32_e32 v211, v21, v251
	v_fma_f32 v212, v20, v253, v226
	v_fma_f32 v209, v20, v211, v227
	v_fma_f32 v212, -v21, v211, v212
	v_fmac_f32_e32 v209, v21, v253
	v_cndmask_b32_e64 v195, v251, v253, s[40:41]
	v_cndmask_b32_e64 v196, v252, v211, s[40:41]
	v_cndmask_b32_e64 v216, v61, v173, s[40:41]
	v_cndmask_b32_e64 v217, v93, v174, s[40:41]
	v_cndmask_b32_e64 v218, v173, v61, s[40:41]
	v_cndmask_b32_e64 v219, v174, v93, s[40:41]
	v_fma_f32 v213, v12, v249, v216
	v_fma_f32 v214, v12, v250, v217
	v_fma_f32 v213, -v13, v250, v213
	v_fmac_f32_e32 v214, v13, v249
	v_fma_f32 v215, v12, v213, v218
	v_fma_f32 v248, v12, v214, v219
	v_fma_f32 v215, -v13, v214, v215
	v_fmac_f32_e32 v248, v13, v213
	v_cndmask_b32_e64 v189, v249, v213, s[40:41]
	v_cndmask_b32_e64 v190, v250, v214, s[40:41]
	v_cndmask_b32_e64 v224, v77, v181, s[40:41]
	v_cndmask_b32_e64 v225, v109, v182, s[40:41]
	v_cndmask_b32_e64 v226, v181, v77, s[40:41]
	v_cndmask_b32_e64 v227, v182, v109, s[40:41]
	v_fma_f32 v251, v20, v212, v224
	v_fma_f32 v252, v20, v209, v225
	v_fma_f32 v251, -v21, v209, v251
	v_fmac_f32_e32 v252, v21, v212
	v_fma_f32 v253, v20, v251, v226
	v_fma_f32 v211, v20, v252, v227
	v_fma_f32 v253, -v21, v252, v253
	v_fmac_f32_e32 v211, v21, v251
	v_cndmask_b32_e64 v197, v212, v251, s[40:41]
	v_cndmask_b32_e64 v198, v209, v252, s[40:41]
	v_mov_b32_e32 v22, v215
	v_mov_b32_e32 v23, v248
	v_mov_b32_e32 v24, v253
	v_mov_b32_e32 v25, v211
	v_fmac_f32_e32 v46, v6, v183
	v_fmac_f32_e32 v78, v6, v184
	v_fma_f32 v46, -v7, v184, v46
	v_fmac_f32_e32 v78, v7, v183
	v_fmac_f32_e32 v47, v8, v183
	v_fmac_f32_e32 v79, v8, v184
	v_fma_f32 v47, -v9, v184, v47
	v_fmac_f32_e32 v79, v9, v183
	v_fmac_f32_e32 v48, v10, v183
	v_fmac_f32_e32 v80, v10, v184
	v_fma_f32 v48, -v11, v184, v48
	v_fmac_f32_e32 v80, v11, v183
	v_fmac_f32_e32 v49, v12, v183
	v_fmac_f32_e32 v81, v12, v184
	v_fma_f32 v49, -v13, v184, v49
	v_fmac_f32_e32 v81, v13, v183
	v_fmac_f32_e32 v50, v6, v185
	v_fmac_f32_e32 v82, v6, v186
	v_fma_f32 v50, -v7, v186, v50
	v_fmac_f32_e32 v82, v7, v185
	v_fmac_f32_e32 v51, v8, v185
	v_fmac_f32_e32 v83, v8, v186
	v_fma_f32 v51, -v9, v186, v51
	v_fmac_f32_e32 v83, v9, v185
	v_fmac_f32_e32 v52, v10, v185
	v_fmac_f32_e32 v84, v10, v186
	v_fma_f32 v52, -v11, v186, v52
	v_fmac_f32_e32 v84, v11, v185
	v_fmac_f32_e32 v53, v12, v185
	v_fmac_f32_e32 v85, v12, v186
	v_fma_f32 v53, -v13, v186, v53
	v_fmac_f32_e32 v85, v13, v185
	v_fmac_f32_e32 v54, v6, v187
	v_fmac_f32_e32 v86, v6, v188
	v_fma_f32 v54, -v7, v188, v54
	v_fmac_f32_e32 v86, v7, v187
	v_fmac_f32_e32 v55, v8, v187
	v_fmac_f32_e32 v87, v8, v188
	v_fma_f32 v55, -v9, v188, v55
	v_fmac_f32_e32 v87, v9, v187
	v_fmac_f32_e32 v56, v10, v187
	v_fmac_f32_e32 v88, v10, v188
	v_fma_f32 v56, -v11, v188, v56
	v_fmac_f32_e32 v88, v11, v187
	v_fmac_f32_e32 v57, v12, v187
	v_fmac_f32_e32 v89, v12, v188
	v_fma_f32 v57, -v13, v188, v57
	v_fmac_f32_e32 v89, v13, v187
	v_fmac_f32_e32 v58, v6, v189
	v_fmac_f32_e32 v90, v6, v190
	v_fma_f32 v58, -v7, v190, v58
	v_fmac_f32_e32 v90, v7, v189
	v_fmac_f32_e32 v59, v8, v189
	v_fmac_f32_e32 v91, v8, v190
	v_fma_f32 v59, -v9, v190, v59
	v_fmac_f32_e32 v91, v9, v189
	v_fmac_f32_e32 v60, v10, v189
	v_fmac_f32_e32 v92, v10, v190
	v_fma_f32 v60, -v11, v190, v60
	v_fmac_f32_e32 v92, v11, v189
	v_fmac_f32_e32 v61, v12, v189
	v_fmac_f32_e32 v93, v12, v190
	v_fma_f32 v61, -v13, v190, v61
	v_fmac_f32_e32 v93, v13, v189
	v_fmac_f32_e32 v62, v14, v191
	v_fmac_f32_e32 v94, v14, v192
	v_fma_f32 v62, -v15, v192, v62
	v_fmac_f32_e32 v94, v15, v191
	v_fmac_f32_e32 v63, v16, v191
	v_fmac_f32_e32 v95, v16, v192
	v_fma_f32 v63, -v17, v192, v63
	v_fmac_f32_e32 v95, v17, v191
	v_fmac_f32_e32 v64, v18, v191
	v_fmac_f32_e32 v96, v18, v192
	v_fma_f32 v64, -v19, v192, v64
	v_fmac_f32_e32 v96, v19, v191
	v_fmac_f32_e32 v65, v20, v191
	v_fmac_f32_e32 v97, v20, v192
	v_fma_f32 v65, -v21, v192, v65
	v_fmac_f32_e32 v97, v21, v191
	v_fmac_f32_e32 v66, v14, v193
	v_fmac_f32_e32 v98, v14, v194
	v_fma_f32 v66, -v15, v194, v66
	v_fmac_f32_e32 v98, v15, v193
	v_fmac_f32_e32 v67, v16, v193
	v_fmac_f32_e32 v99, v16, v194
	v_fma_f32 v67, -v17, v194, v67
	v_fmac_f32_e32 v99, v17, v193
	v_fmac_f32_e32 v68, v18, v193
	v_fmac_f32_e32 v100, v18, v194
	v_fma_f32 v68, -v19, v194, v68
	v_fmac_f32_e32 v100, v19, v193
	v_fmac_f32_e32 v69, v20, v193
	v_fmac_f32_e32 v101, v20, v194
	v_fma_f32 v69, -v21, v194, v69
	v_fmac_f32_e32 v101, v21, v193
	v_fmac_f32_e32 v70, v14, v195
	v_fmac_f32_e32 v102, v14, v196
	v_fma_f32 v70, -v15, v196, v70
	v_fmac_f32_e32 v102, v15, v195
	v_fmac_f32_e32 v71, v16, v195
	v_fmac_f32_e32 v103, v16, v196
	v_fma_f32 v71, -v17, v196, v71
	v_fmac_f32_e32 v103, v17, v195
	v_fmac_f32_e32 v72, v18, v195
	v_fmac_f32_e32 v104, v18, v196
	v_fma_f32 v72, -v19, v196, v72
	v_fmac_f32_e32 v104, v19, v195
	v_fmac_f32_e32 v73, v20, v195
	v_fmac_f32_e32 v105, v20, v196
	v_fma_f32 v73, -v21, v196, v73
	v_fmac_f32_e32 v105, v21, v195
	v_fmac_f32_e32 v74, v14, v197
	v_fmac_f32_e32 v106, v14, v198
	v_fma_f32 v74, -v15, v198, v74
	v_fmac_f32_e32 v106, v15, v197
	v_fmac_f32_e32 v75, v16, v197
	v_fmac_f32_e32 v107, v16, v198
	v_fma_f32 v75, -v17, v198, v75
	v_fmac_f32_e32 v107, v17, v197
	v_fmac_f32_e32 v76, v18, v197
	v_fmac_f32_e32 v108, v18, v198
	v_fma_f32 v76, -v19, v198, v76
	v_fmac_f32_e32 v108, v19, v197
	v_fmac_f32_e32 v77, v20, v197
	v_fmac_f32_e32 v109, v20, v198
	v_fma_f32 v77, -v21, v198, v77
	v_fmac_f32_e32 v109, v21, v197
	v_cvt_pk_bf16_f32 v216, v46, v47
	v_cvt_pk_bf16_f32 v217, v48, v49
	ds_write_b64 v200, v[216:217] offset:0
	v_cvt_pk_bf16_f32 v218, v50, v51
	v_cvt_pk_bf16_f32 v219, v52, v53
	ds_write_b64 v200, v[218:219] offset:16
	v_cvt_pk_bf16_f32 v220, v54, v55
	v_cvt_pk_bf16_f32 v221, v56, v57
	ds_write_b64 v200, v[220:221] offset:32
	v_cvt_pk_bf16_f32 v222, v58, v59
	v_cvt_pk_bf16_f32 v223, v60, v61
	ds_write_b64 v200, v[222:223] offset:48
	v_cvt_pk_bf16_f32 v224, v62, v63
	v_cvt_pk_bf16_f32 v225, v64, v65
	ds_write_b64 v200, v[224:225] offset:2048
	v_cvt_pk_bf16_f32 v226, v66, v67
	v_cvt_pk_bf16_f32 v227, v68, v69
	ds_write_b64 v200, v[226:227] offset:2064
	v_cvt_pk_bf16_f32 v228, v70, v71
	v_cvt_pk_bf16_f32 v229, v72, v73
	ds_write_b64 v200, v[228:229] offset:2080
	v_cvt_pk_bf16_f32 v230, v74, v75
	v_cvt_pk_bf16_f32 v231, v76, v77
	ds_write_b64 v200, v[230:231] offset:2096
	v_cvt_pk_bf16_f32 v232, v78, v79
	v_cvt_pk_bf16_f32 v233, v80, v81
	ds_write_b64 v200, v[232:233] offset:4096
	v_cvt_pk_bf16_f32 v234, v82, v83
	v_cvt_pk_bf16_f32 v235, v84, v85
	ds_write_b64 v200, v[234:235] offset:4112
	v_cvt_pk_bf16_f32 v236, v86, v87
	v_cvt_pk_bf16_f32 v237, v88, v89
	ds_write_b64 v200, v[236:237] offset:4128
	v_cvt_pk_bf16_f32 v238, v90, v91
	v_cvt_pk_bf16_f32 v239, v92, v93
	ds_write_b64 v200, v[238:239] offset:4144
	v_cvt_pk_bf16_f32 v240, v94, v95
	v_cvt_pk_bf16_f32 v241, v96, v97
	ds_write_b64 v200, v[240:241] offset:6144
	v_cvt_pk_bf16_f32 v242, v98, v99
	v_cvt_pk_bf16_f32 v243, v100, v101
	ds_write_b64 v200, v[242:243] offset:6160
	v_cvt_pk_bf16_f32 v244, v102, v103
	v_cvt_pk_bf16_f32 v245, v104, v105
	ds_write_b64 v200, v[244:245] offset:6176
	v_cvt_pk_bf16_f32 v246, v106, v107
	v_cvt_pk_bf16_f32 v247, v108, v109
	ds_write_b64 v200, v[246:247] offset:6192
	s_waitcnt lgkmcnt(0)
	ds_read_b64_tr_b16 v[216:217], v201 offset:0
	ds_read_b64_tr_b16 v[218:219], v201 offset:256
	ds_read_b64_tr_b16 v[220:221], v201 offset:1024
	ds_read_b64_tr_b16 v[222:223], v201 offset:1280
	ds_read_b64_tr_b16 v[224:225], v201 offset:2048
	ds_read_b64_tr_b16 v[226:227], v201 offset:2304
	ds_read_b64_tr_b16 v[228:229], v201 offset:3072
	ds_read_b64_tr_b16 v[230:231], v201 offset:3328
	ds_read_b64_tr_b16 v[232:233], v201 offset:4096
	ds_read_b64_tr_b16 v[234:235], v201 offset:4352
	ds_read_b64_tr_b16 v[236:237], v201 offset:5120
	ds_read_b64_tr_b16 v[238:239], v201 offset:5376
	ds_read_b64_tr_b16 v[240:241], v201 offset:6144
	ds_read_b64_tr_b16 v[242:243], v201 offset:6400
	ds_read_b64_tr_b16 v[244:245], v201 offset:7168
	ds_read_b64_tr_b16 v[246:247], v201 offset:7424
	s_waitcnt lgkmcnt(14)
	v_mfma_f32_32x32x16_bf16 v[110:125], v[216:219], v[134:137], v[110:125]
	s_waitcnt lgkmcnt(12)
	v_mfma_f32_32x32x16_bf16 v[110:125], v[220:223], v[138:141], v[110:125]
	s_waitcnt lgkmcnt(10)
	v_mfma_f32_32x32x16_bf16 v[110:125], v[224:227], v[142:145], v[110:125]
	s_waitcnt lgkmcnt(8)
	v_mfma_f32_32x32x16_bf16 v[110:125], v[228:231], v[146:149], v[110:125]
	s_waitcnt lgkmcnt(6)
	v_mfma_f32_32x32x16_bf16 v[110:125], v[232:235], v[150:153], v[110:125]
	s_waitcnt lgkmcnt(4)
	v_mfma_f32_32x32x16_bf16 v[110:125], v[236:239], v[154:157], v[110:125]
	s_waitcnt lgkmcnt(2)
	v_mfma_f32_32x32x16_bf16 v[110:125], v[240:243], v[158:161], v[110:125]
	s_waitcnt lgkmcnt(0)
	v_mfma_f32_32x32x16_bf16 v[110:125], v[244:247], v[162:165], v[110:125]
	s_nop 7
	s_nop 3
	s_mov_b64 exec, s[44:45]
	ds_write_b32 v202, v110 offset:0
	ds_write_b32 v202, v111 offset:64
	ds_write_b32 v202, v112 offset:128
	ds_write_b32 v202, v113 offset:192
	ds_write_b32 v202, v114 offset:512
	ds_write_b32 v202, v115 offset:576
	ds_write_b32 v202, v116 offset:640
	ds_write_b32 v202, v117 offset:704
	ds_write_b32 v202, v118 offset:1024
	ds_write_b32 v202, v119 offset:1088
	ds_write_b32 v202, v120 offset:1152
	ds_write_b32 v202, v121 offset:1216
	ds_write_b32 v202, v122 offset:1536
	ds_write_b32 v202, v123 offset:1600
	ds_write_b32 v202, v124 offset:1664
	ds_write_b32 v202, v125 offset:1728
	s_mov_b64 exec, -1
	s_waitcnt lgkmcnt(0)
	ds_read_b128 v[216:219], v203
	ds_read_b128 v[220:223], v203 offset:16
	s_waitcnt lgkmcnt(0)
	v_mul_f32_e32 v224, 0x3d372713, v216
	v_mul_f32_e32 v225, 0x3d372713, v217
	v_mul_f32_e32 v226, 0x3d372713, v218
	v_mul_f32_e32 v227, 0x3d372713, v219
	v_mul_f32_e32 v228, 0x3d372713, v220
	v_mul_f32_e32 v229, 0x3d372713, v221
	v_mul_f32_e32 v230, 0x3d372713, v222
	v_mul_f32_e32 v231, 0x3d372713, v223
	v_mul_f32_e32 v224, v216, v224
	v_mul_f32_e32 v225, v217, v225
	v_mul_f32_e32 v226, v218, v226
	v_mul_f32_e32 v227, v219, v227
	v_mul_f32_e32 v228, v220, v228
	v_mul_f32_e32 v229, v221, v229
	v_mul_f32_e32 v230, v222, v230
	v_mul_f32_e32 v231, v223, v231
	v_fma_f32 v224, v216, v224, v216
	v_fma_f32 v225, v217, v225, v217
	v_fma_f32 v226, v218, v226, v218
	v_fma_f32 v227, v219, v227, v219
	v_fma_f32 v228, v220, v228, v220
	v_fma_f32 v229, v221, v229, v221
	v_fma_f32 v230, v222, v230, v222
	v_fma_f32 v231, v223, v231, v223
	v_mul_f32_e32 v224, 0x3f4c422a, v224
	v_mul_f32_e32 v225, 0x3f4c422a, v225
	v_mul_f32_e32 v226, 0x3f4c422a, v226
	v_mul_f32_e32 v227, 0x3f4c422a, v227
	v_mul_f32_e32 v228, 0x3f4c422a, v228
	v_mul_f32_e32 v229, 0x3f4c422a, v229
	v_mul_f32_e32 v230, 0x3f4c422a, v230
	v_mul_f32_e32 v231, 0x3f4c422a, v231
	v_add_f32_e32 v224, v224, v224
	v_add_f32_e32 v225, v225, v225
	v_add_f32_e32 v226, v226, v226
	v_add_f32_e32 v227, v227, v227
	v_add_f32_e32 v228, v228, v228
	v_add_f32_e32 v229, v229, v229
	v_add_f32_e32 v230, v230, v230
	v_add_f32_e32 v231, v231, v231
	v_mul_f32_e32 v224, 0xbfb8aa3b, v224
	v_mul_f32_e32 v225, 0xbfb8aa3b, v225
	v_mul_f32_e32 v226, 0xbfb8aa3b, v226
	v_mul_f32_e32 v227, 0xbfb8aa3b, v227
	v_mul_f32_e32 v228, 0xbfb8aa3b, v228
	v_mul_f32_e32 v229, 0xbfb8aa3b, v229
	v_mul_f32_e32 v230, 0xbfb8aa3b, v230
	v_mul_f32_e32 v231, 0xbfb8aa3b, v231
	v_exp_f32_e32 v224, v224
	v_exp_f32_e32 v225, v225
	v_exp_f32_e32 v226, v226
	v_exp_f32_e32 v227, v227
	v_exp_f32_e32 v228, v228
	v_exp_f32_e32 v229, v229
	v_exp_f32_e32 v230, v230
	v_exp_f32_e32 v231, v231
	s_nop 0
	v_add_f32_e32 v224, 1.0, v224
	v_add_f32_e32 v225, 1.0, v225
	v_add_f32_e32 v226, 1.0, v226
	v_add_f32_e32 v227, 1.0, v227
	v_add_f32_e32 v228, 1.0, v228
	v_add_f32_e32 v229, 1.0, v229
	v_add_f32_e32 v230, 1.0, v230
	v_add_f32_e32 v231, 1.0, v231
	v_rcp_f32_e32 v224, v224
	v_rcp_f32_e32 v225, v225
	v_rcp_f32_e32 v226, v226
	v_rcp_f32_e32 v227, v227
	v_rcp_f32_e32 v228, v228
	v_rcp_f32_e32 v229, v229
	v_rcp_f32_e32 v230, v230
	v_rcp_f32_e32 v231, v231
	s_nop 0
	v_mul_f32_e32 v224, v216, v224
	v_mul_f32_e32 v225, v217, v225
	v_mul_f32_e32 v226, v218, v226
	v_mul_f32_e32 v227, v219, v227
	v_mul_f32_e32 v228, v220, v228
	v_mul_f32_e32 v229, v221, v229
	v_mul_f32_e32 v230, v222, v230
	v_mul_f32_e32 v231, v223, v231
	v_cvt_pk_bf16_f32 v232, v224, v225
	v_cvt_pk_bf16_f32 v233, v226, v227
	v_cvt_pk_bf16_f32 v234, v228, v229
	v_cvt_pk_bf16_f32 v235, v230, v231
	s_add_u32 s70, s60, 0x60000
	s_addc_u32 s71, s61, 0
	global_store_dwordx4 v205, v[232:235], s[70:71]
	s_cmp_eq_u32 s15, 31
	s_cbranch_scc0 .Lpc_nofin
	s_mov_b64 exec, s[42:43]
	global_store_dword v206, v22, s[64:65]
	global_store_dword v206, v24, s[64:65] offset:128
	global_store_dword v206, v23, s[66:67]
	global_store_dword v206, v25, s[66:67] offset:128
	s_mov_b64 exec, -1
.Lpc_nofin:
	s_addk_i32 s46, 0x100
	s_cmpk_lt_i32 s46, 0x400
	s_cbranch_scc1 .Lpc_item
	s_branch .LBB0_1414
.Lpc_compiled:
	s_load_dwordx4 s[28:31], s[2:3], 0xc8
	s_load_dwordx2 s[0:1], s[2:3], 0xa0
	v_and_b32_e32 v3, 63, v2
	v_lshlrev_b32_e32 v96, 4, v3
	v_and_b32_e32 v94, 31, v2
	s_waitcnt lgkmcnt(0)
	s_add_u32 s2, s30, 0x5200000
	s_addc_u32 s3, s31, 0
	s_add_u32 s40, s30, 0x600000
	s_addc_u32 s41, s31, 0
	s_ashr_i32 s42, s6, 6
	v_cmp_lt_u32_e64 s[6:7], 31, v3
	v_mbcnt_hi_u32_b32 v3, -1, v1
	s_add_u32 s26, s30, 0x30000
	v_and_b32_e32 v10, 64, v3
	s_addc_u32 s27, s31, 0
	s_lshl_b32 s8, s42, 13
	v_xor_b32_e32 v9, 32, v3
	v_add_u32_e32 v10, 64, v10
	s_add_i32 s33, s8, 0
	v_cmp_lt_i32_e32 vcc, v9, v10
	v_and_b32_e32 v6, 3, v2
	v_lshrrev_b32_e32 v7, 2, v2
	v_bfe_u32 v8, v2, 5, 1
	v_mov_b32_e32 v97, 0
	v_cndmask_b32_e32 v3, v3, v9, vcc
	v_lshl_add_u32 v206, v94, 6, s33
	s_movk_i32 s10, 0xffc4
	v_bfe_u32 v104, v2, 1, 5
	v_lshlrev_b32_e32 v2, 3, v2
	v_lshl_add_u64 v[4:5], s[30:31], 0, v[96:97]
	s_mov_b64 s[8:9], 0x140000
	v_lshlrev_b32_e32 v167, 2, v3
	v_mad_i32_i24 v9, v94, s10, v206
	v_and_or_b32 v3, v7, 4, v6
	s_mov_b64 s[10:11], 0x1c0000
	v_and_b32_e32 v2, 8, v2
	v_lshl_add_u64 v[98:99], v[4:5], 0, s[8:9]
	v_lshlrev_b32_e32 v6, 3, v3
	v_lshl_add_u64 v[102:103], v[4:5], 0, s[10:11]
	v_lshlrev_b32_e32 v3, 6, v104
	v_lshlrev_b32_e32 v5, 2, v2
	v_lshlrev_b32_e32 v96, 1, v2
	v_lshlrev_b32_e32 v100, 3, v8
	v_add3_u32 v207, s33, v3, v5
	v_lshl_add_u64 v[2:3], s[30:31], 0, v[96:97]
	s_mov_b64 s[10:11], 0xd600000
	v_lshl_add_u64 v[106:107], v[2:3], 0, s[10:11]
	v_or_b32_e32 v2, 2, v100
	v_cmp_eq_u32_e64 s[12:13], v2, v94
	v_or_b32_e32 v2, 4, v100
	v_or_b32_e32 v3, 1, v100
	v_cmp_eq_u32_e64 s[16:17], v2, v94
	v_or_b32_e32 v2, 6, v100
	v_cmp_eq_u32_e64 s[14:15], v3, v94
	v_or_b32_e32 v3, 3, v100
	v_cmp_eq_u32_e64 s[20:21], v2, v94
	v_or_b32_e32 v2, 7, v100
	v_cmp_eq_u32_e64 s[18:19], v3, v94
	v_or_b32_e32 v3, 5, v100
	v_cmp_eq_u32_e64 s[24:25], v2, v94
	v_and_or_b32 v2, v7, 3, v100
	v_lshlrev_b32_e32 v96, 2, v94
	v_cmp_eq_u32_e64 s[22:23], v3, v94
	v_lshl_add_u32 v5, v2, 6, s33
	v_lshl_add_u64 v[2:3], s[28:29], 0, v[96:97]
	s_mov_b64 s[28:29], 0x6084000
	v_lshlrev_b32_e32 v4, 8, v8
	v_lshl_add_u64 v[114:115], v[2:3], 0, s[28:29]
	s_mov_b64 s[28:29], 0x6094000
	s_mov_b32 s43, 0
	v_lshlrev_b32_e32 v101, 1, v94
	v_mov_b32_e32 v95, v97
	v_cmp_gt_u32_e64 s[8:9], 16, v94
	v_cmp_eq_u32_e64 s[10:11], v100, v94
	v_mov_b32_e32 v105, v97
	v_or_b32_e32 v108, 32, v104
	v_mov_b32_e32 v109, v97
	v_or_b32_e32 v110, 64, v104
	v_mov_b32_e32 v111, v97
	v_or_b32_e32 v112, 0x60, v104
	v_mov_b32_e32 v113, v97
	v_lshl_add_u64 v[116:117], v[2:3], 0, s[28:29]
	v_lshlrev_b32_e32 v96, 1, v100
	s_mov_b32 s44, 0x5040100
	s_mov_b32 s45, 0x20000
	s_mov_b32 s46, 0x40000
	s_mov_b32 s47, 0x60000
	s_xor_b64 s[28:29], s[6:7], -1
	v_add_u32_e32 v208, v5, v6
	v_add_u32_e32 v209, v9, v4
	v_readlane_b32 s48, v255, 7
	s_branch .LBB0_1389
